# S5 role LDS-read hoist + vmcnt restructure, rescheduled RWKV scan body, attention softmax bpermute->permlane swaps
# speedup vs baseline: 1.0210x; 1.0210x over previous
.LBB0_578:
	s_nop 0
	v_add_u32_e32 v116, s47, v190
	v_add_u32_e32 v114, 64, v116
	v_add_u32_e32 v116, 0x60, v116
	v_add_u32_e32 v122, s47, v202
	s_add_i32 s58, s47, 64
	v_ashrrev_i32_e32 v115, 31, v114
	v_ashrrev_i32_e32 v117, 31, v116
	v_ashrrev_i32_e32 v123, 31, v122
	v_lshlrev_b64 v[114:115], 12, v[114:115]
	v_lshlrev_b64 v[116:117], 12, v[116:117]
	v_lshlrev_b64 v[122:123], 7, v[122:123]
	s_lshl_b64 s[0:1], s[58:59], 1
	v_lshl_add_u64 v[114:115], v[194:195], 0, v[114:115]
	v_lshl_add_u64 v[118:119], v[194:195], 0, v[116:117]
	v_lshl_add_u64 v[122:123], v[198:199], 0, v[122:123]
	v_lshl_add_u64 v[126:127], v[200:201], 0, s[0:1]
	v_lshl_add_u64 v[130:131], v[204:205], 0, s[0:1]
	global_load_dwordx4 v[114:117], v[114:115], off
	s_nop 0
	global_load_dwordx4 v[118:121], v[118:119], off
	s_nop 0
	global_load_dwordx4 v[122:125], v[122:123], off
	s_nop 0
	global_load_dwordx4 v[126:129], v[126:127], off
	v_max_f32_e32 v223, v151, v151
	global_load_dwordx4 v[130:133], v[130:131], off
	v_max_f32_e32 v224, v150, v150
	v_max_f32_e32 v223, v224, v223
	v_max3_f32 v223, v223, v152, v153
	v_max3_f32 v223, v223, v154, v155
	v_max3_f32 v223, v223, v156, v157
	v_max3_f32 v223, v223, v158, v159
	v_max3_f32 v223, v223, v160, v161
	v_max3_f32 v223, v223, v162, v163
	v_max3_f32 v223, v223, v164, v165
	v_mov_b32_e32 v224, v223
	s_waitcnt lgkmcnt(0)
	s_nop 0
	v_permlane16_swap_b32_e32 v223, v224
	v_max_f32_e32 v223, v223, v224
	v_mov_b32_e32 v224, v223
	s_nop 1
	v_permlane32_swap_b32_e32 v223, v224
	v_max3_f32 v223, v206, v223, v224
	v_sub_f32_e32 v206, v206, v223
	v_exp_f32_e32 v206, v206
	s_nop 0
	v_cmp_neq_f32_e32 vcc, 1.0, v206
	s_cbranch_vccz .LBB0_580
	v_pk_mul_f32 v[64:65], v[64:65], v[206:207] op_sel_hi:[1,0]
	v_pk_mul_f32 v[62:63], v[62:63], v[206:207] op_sel_hi:[1,0]
	v_pk_mul_f32 v[60:61], v[60:61], v[206:207] op_sel_hi:[1,0]
	v_pk_mul_f32 v[58:59], v[58:59], v[206:207] op_sel_hi:[1,0]
	v_pk_mul_f32 v[56:57], v[56:57], v[206:207] op_sel_hi:[1,0]
	v_pk_mul_f32 v[54:55], v[54:55], v[206:207] op_sel_hi:[1,0]
	v_pk_mul_f32 v[52:53], v[52:53], v[206:207] op_sel_hi:[1,0]
	v_pk_mul_f32 v[50:51], v[50:51], v[206:207] op_sel_hi:[1,0]
	v_pk_mul_f32 v[48:49], v[48:49], v[206:207] op_sel_hi:[1,0]
	v_pk_mul_f32 v[46:47], v[46:47], v[206:207] op_sel_hi:[1,0]
	v_pk_mul_f32 v[44:45], v[44:45], v[206:207] op_sel_hi:[1,0]
	v_pk_mul_f32 v[42:43], v[42:43], v[206:207] op_sel_hi:[1,0]
	v_pk_mul_f32 v[40:41], v[40:41], v[206:207] op_sel_hi:[1,0]
	v_pk_mul_f32 v[38:39], v[38:39], v[206:207] op_sel_hi:[1,0]
	v_pk_mul_f32 v[36:37], v[36:37], v[206:207] op_sel_hi:[1,0]
	v_pk_mul_f32 v[34:35], v[34:35], v[206:207] op_sel_hi:[1,0]
.LBB0_580:
	v_max_f32_e32 v224, v135, v135
	v_max_f32_e32 v225, v134, v134
	v_max_f32_e32 v224, v225, v224
	v_max3_f32 v224, v224, v136, v137
	v_max3_f32 v224, v224, v138, v139
	v_max3_f32 v224, v224, v140, v141
	v_max3_f32 v224, v224, v146, v147
	v_max3_f32 v224, v224, v148, v149
	v_max3_f32 v224, v224, v142, v143
	v_max3_f32 v224, v224, v144, v145
	v_mov_b32_e32 v225, v224
	s_waitcnt lgkmcnt(0)
	s_nop 0
	v_permlane16_swap_b32_e32 v224, v225
	v_max_f32_e32 v224, v224, v225
	v_mov_b32_e32 v225, v224
	s_nop 1
	v_permlane32_swap_b32_e32 v224, v225
	v_max3_f32 v224, v208, v224, v225
	v_sub_f32_e32 v208, v208, v224
	v_exp_f32_e32 v208, v208
	s_nop 0
	v_cmp_neq_f32_e32 vcc, 1.0, v208
	s_cbranch_vccz .LBB0_582
	v_pk_mul_f32 v[32:33], v[32:33], v[208:209] op_sel_hi:[1,0]
	v_pk_mul_f32 v[30:31], v[30:31], v[208:209] op_sel_hi:[1,0]
	v_pk_mul_f32 v[28:29], v[28:29], v[208:209] op_sel_hi:[1,0]
	v_pk_mul_f32 v[26:27], v[26:27], v[208:209] op_sel_hi:[1,0]
	v_pk_mul_f32 v[24:25], v[24:25], v[208:209] op_sel_hi:[1,0]
	v_pk_mul_f32 v[22:23], v[22:23], v[208:209] op_sel_hi:[1,0]
	v_pk_mul_f32 v[20:21], v[20:21], v[208:209] op_sel_hi:[1,0]
	v_pk_mul_f32 v[18:19], v[18:19], v[208:209] op_sel_hi:[1,0]
	v_pk_mul_f32 v[16:17], v[16:17], v[208:209] op_sel_hi:[1,0]
	v_pk_mul_f32 v[14:15], v[14:15], v[208:209] op_sel_hi:[1,0]
	v_pk_mul_f32 v[12:13], v[12:13], v[208:209] op_sel_hi:[1,0]
	v_pk_mul_f32 v[10:11], v[10:11], v[208:209] op_sel_hi:[1,0]
	v_pk_mul_f32 v[8:9], v[8:9], v[208:209] op_sel_hi:[1,0]
	v_pk_mul_f32 v[6:7], v[6:7], v[208:209] op_sel_hi:[1,0]
	v_pk_mul_f32 v[4:5], v[4:5], v[208:209] op_sel_hi:[1,0]
	v_pk_mul_f32 v[2:3], v[2:3], v[208:209] op_sel_hi:[1,0]

.LBB0_592:
	s_nop 1
	v_max_f32_e32 v74, v127, v127
	v_max_f32_e32 v75, v126, v126
	v_max_f32_e32 v74, v75, v74
	v_max3_f32 v74, v74, v128, v129
	v_max3_f32 v74, v74, v130, v131
	v_max3_f32 v74, v74, v132, v133
	v_max3_f32 v74, v74, v134, v135
	v_max3_f32 v74, v74, v136, v137
	v_max3_f32 v74, v74, v70, v71
	v_max3_f32 v74, v74, v72, v73
	v_mov_b32_e32 v75, v74
	s_waitcnt lgkmcnt(0)
	s_nop 0
	v_permlane16_swap_b32_e32 v74, v75
	v_max_f32_e32 v74, v74, v75
	v_mov_b32_e32 v75, v74
	s_nop 1
	v_permlane32_swap_b32_e32 v74, v75
	v_max3_f32 v74, v223, v74, v75
	v_sub_f32_e32 v75, v223, v74
	v_exp_f32_e32 v78, v75
	s_nop 0
	v_cmp_neq_f32_e32 vcc, 1.0, v78
	s_cbranch_vccz .LBB0_594
	v_pk_mul_f32 v[64:65], v[64:65], v[78:79] op_sel_hi:[1,0]
	v_pk_mul_f32 v[62:63], v[62:63], v[78:79] op_sel_hi:[1,0]
	v_pk_mul_f32 v[60:61], v[60:61], v[78:79] op_sel_hi:[1,0]
	v_pk_mul_f32 v[58:59], v[58:59], v[78:79] op_sel_hi:[1,0]
	v_pk_mul_f32 v[56:57], v[56:57], v[78:79] op_sel_hi:[1,0]
	v_pk_mul_f32 v[54:55], v[54:55], v[78:79] op_sel_hi:[1,0]
	v_pk_mul_f32 v[52:53], v[52:53], v[78:79] op_sel_hi:[1,0]
	v_pk_mul_f32 v[50:51], v[50:51], v[78:79] op_sel_hi:[1,0]
	v_pk_mul_f32 v[48:49], v[48:49], v[78:79] op_sel_hi:[1,0]
	v_pk_mul_f32 v[46:47], v[46:47], v[78:79] op_sel_hi:[1,0]
	v_pk_mul_f32 v[44:45], v[44:45], v[78:79] op_sel_hi:[1,0]
	v_pk_mul_f32 v[42:43], v[42:43], v[78:79] op_sel_hi:[1,0]
	v_pk_mul_f32 v[40:41], v[40:41], v[78:79] op_sel_hi:[1,0]
	v_pk_mul_f32 v[38:39], v[38:39], v[78:79] op_sel_hi:[1,0]
	v_pk_mul_f32 v[36:37], v[36:37], v[78:79] op_sel_hi:[1,0]
	v_pk_mul_f32 v[34:35], v[34:35], v[78:79] op_sel_hi:[1,0]
.LBB0_594:
	v_max_f32_e32 v75, v115, v115
	v_max_f32_e32 v76, v114, v114
	v_max_f32_e32 v75, v76, v75
	v_max3_f32 v75, v75, v116, v117
	v_max3_f32 v75, v75, v118, v119
	v_max3_f32 v75, v75, v120, v121
	v_max3_f32 v75, v75, v122, v123
	v_max3_f32 v75, v75, v124, v125
	v_max3_f32 v75, v75, v66, v67
	v_max3_f32 v75, v75, v68, v69
	v_mov_b32_e32 v76, v75
	s_waitcnt lgkmcnt(0)
	s_nop 0
	v_permlane16_swap_b32_e32 v75, v76
	v_max_f32_e32 v75, v75, v76
	v_mov_b32_e32 v76, v75
	s_nop 1
	v_permlane32_swap_b32_e32 v75, v76
	v_max3_f32 v79, v224, v75, v76
	v_sub_f32_e32 v75, v224, v79
	v_exp_f32_e32 v80, v75
	s_nop 0
	v_cmp_neq_f32_e32 vcc, 1.0, v80
	s_cbranch_vccz .LBB0_564
	v_pk_mul_f32 v[32:33], v[32:33], v[80:81] op_sel_hi:[1,0]
	v_pk_mul_f32 v[30:31], v[30:31], v[80:81] op_sel_hi:[1,0]
	v_pk_mul_f32 v[28:29], v[28:29], v[80:81] op_sel_hi:[1,0]
	v_pk_mul_f32 v[26:27], v[26:27], v[80:81] op_sel_hi:[1,0]
	v_pk_mul_f32 v[24:25], v[24:25], v[80:81] op_sel_hi:[1,0]
	v_pk_mul_f32 v[22:23], v[22:23], v[80:81] op_sel_hi:[1,0]
	v_pk_mul_f32 v[20:21], v[20:21], v[80:81] op_sel_hi:[1,0]
	v_pk_mul_f32 v[18:19], v[18:19], v[80:81] op_sel_hi:[1,0]
	v_pk_mul_f32 v[16:17], v[16:17], v[80:81] op_sel_hi:[1,0]
	v_pk_mul_f32 v[14:15], v[14:15], v[80:81] op_sel_hi:[1,0]
	v_pk_mul_f32 v[12:13], v[12:13], v[80:81] op_sel_hi:[1,0]
	v_pk_mul_f32 v[10:11], v[10:11], v[80:81] op_sel_hi:[1,0]
	v_pk_mul_f32 v[8:9], v[8:9], v[80:81] op_sel_hi:[1,0]
	v_pk_mul_f32 v[6:7], v[6:7], v[80:81] op_sel_hi:[1,0]
	v_pk_mul_f32 v[4:5], v[4:5], v[80:81] op_sel_hi:[1,0]
	v_pk_mul_f32 v[2:3], v[2:3], v[80:81] op_sel_hi:[1,0]
	s_branch .LBB0_564

.LBB0_876:
	s_or_b64 exec, exec, s[42:43]
	v_add_f32_e32 v10, v55, v55
	v_mul_f32_e32 v0, v109, v109
	v_mul_f32_e32 v10, v109, v10
	v_fma_f32 v0, v55, v55, -v0
	v_mul_f32_e32 v11, v10, v10
	v_fma_f32 v11, v0, v0, -v11
	v_add_f32_e32 v0, v0, v0
	v_mul_f32_e32 v0, v10, v0
	v_mul_f32_e32 v10, v0, v0
	v_fma_f32 v10, v11, v11, -v10
	v_add_f32_e32 v11, v11, v11
	v_mul_f32_e32 v59, v0, v11
	v_mul_f32_e32 v0, v59, v59
	v_lshlrev_b32_e32 v111, 2, v111
	v_add_f32_e32 v121, v10, v10
	v_cvt_pk_bf16_f32 v6, v6, v7
	v_cvt_pk_bf16_f32 v7, v8, v9
	v_cvt_pk_bf16_f32 v8, v56, v57
	v_cvt_pk_bf16_f32 v9, v16, v17
	v_fma_f32 v56, v10, v10, -v0
	s_waitcnt vmcnt(6)
	v_cvt_pk_bf16_f32 v10, v42, v43
	s_waitcnt vmcnt(5)
	v_cvt_pk_bf16_f32 v16, v34, v35
	v_or_b32_e32 v42, s55, v111
	v_mov_b64_e32 v[34:35], s[22:23]
	v_cvt_pk_bf16_f32 v17, v36, v37
	v_mad_i64_i32 v[36:37], s[42:43], v42, s48, v[34:35]
	v_lshlrev_b32_e32 v0, 1, v58
	v_cvt_pk_bf16_f32 v12, v12, v13
	v_cvt_pk_bf16_f32 v13, v14, v15
	s_waitcnt vmcnt(4)
	v_cvt_pk_bf16_f32 v14, v38, v39
	v_lshl_add_u64 v[36:37], v[36:37], 0, v[0:1]
	v_lshlrev_b32_e32 v122, 1, v54
	v_mov_b32_e32 v123, v1
	v_or_b32_e32 v38, 1, v42
	v_lshl_add_u64 v[36:37], v[36:37], 0, v[122:123]
	s_movk_i32 s2, 0x2000
	v_mad_i64_i32 v[38:39], s[42:43], v38, s48, v[34:35]
	v_cvt_pk_bf16_f32 v15, v40, v41
	v_add_co_u32_e32 v36, vcc, s2, v36
	v_lshl_add_u64 v[38:39], v[38:39], 0, v[0:1]
	v_or_b32_e32 v40, 2, v42
	v_addc_co_u32_e32 v37, vcc, 0, v37, vcc
	v_lshl_add_u64 v[38:39], v[38:39], 0, v[122:123]
	v_mad_i64_i32 v[40:41], s[42:43], v40, s48, v[34:35]
	v_add_co_u32_e32 v38, vcc, s2, v38
	v_lshl_add_u64 v[40:41], v[40:41], 0, v[0:1]
	v_or_b32_e32 v42, 3, v42
	v_addc_co_u32_e32 v39, vcc, 0, v39, vcc
	v_lshl_add_u64 v[40:41], v[40:41], 0, v[122:123]
	v_mad_i64_i32 v[34:35], s[42:43], v42, s48, v[34:35]
	v_add_co_u32_e32 v40, vcc, s2, v40
	v_lshl_add_u64 v[34:35], v[34:35], 0, v[0:1]
	s_nop 0
	v_addc_co_u32_e32 v41, vcc, 0, v41, vcc
	v_lshl_add_u64 v[34:35], v[34:35], 0, v[122:123]
	v_add_co_u32_e32 v34, vcc, s2, v34
	v_readlane_b32 s2, v250, 3
	s_nop 0
	v_addc_co_u32_e32 v35, vcc, 0, v35, vcc
	global_load_ushort v112, v[36:37], off
	global_load_ushort v113, v[38:39], off
	global_load_ushort v114, v[40:41], off
	global_load_ushort v115, v[34:35], off
	s_waitcnt vmcnt(7)
	v_xor_b32_e32 v33, 0x80000000, v33
	v_xor_b32_e32 v32, 0x80000000, v32
	v_xor_b32_e32 v31, 0x80000000, v31
	v_xor_b32_e32 v30, 0x80000000, v30
	s_waitcnt vmcnt(6)
	v_xor_b32_e32 v21, 0x80000000, v21
	v_xor_b32_e32 v20, 0x80000000, v20
	v_xor_b32_e32 v19, 0x80000000, v19
	v_xor_b32_e32 v18, 0x80000000, v18
	s_waitcnt vmcnt(5)
	v_xor_b32_e32 v29, 0x80000000, v29
	v_xor_b32_e32 v28, 0x80000000, v28
	v_xor_b32_e32 v27, 0x80000000, v27
	v_xor_b32_e32 v26, 0x80000000, v26
	s_waitcnt vmcnt(4)
	v_xor_b32_e32 v25, 0x80000000, v25
	v_xor_b32_e32 v24, 0x80000000, v24
	v_xor_b32_e32 v23, 0x80000000, v23
	v_xor_b32_e32 v22, 0x80000000, v22
	v_mul_f32_e32 v58, v59, v121
	v_cvt_pk_bf16_f32 v42, v70, v71
	v_cvt_pk_bf16_f32 v50, v50, v51
	v_cvt_pk_bf16_f32 v51, v52, v53
	v_cvt_pk_bf16_f32 v53, v60, v61
	v_lshl_add_u64 v[60:61], s[56:57], 0, v[0:1]
	v_mul_f32_e32 v70, 0, v55
	s_add_i32 s2, s2, s24
	v_cvt_pk_bf16_f32 v11, v44, v45
	v_cvt_pk_bf16_f32 v18, v18, v19
	v_cvt_pk_bf16_f32 v19, v20, v21
	v_cvt_pk_bf16_f32 v20, v30, v31
	v_cvt_pk_bf16_f32 v21, v32, v33
	v_cvt_pk_bf16_f32 v22, v22, v23
	v_cvt_pk_bf16_f32 v23, v24, v25
	v_cvt_pk_bf16_f32 v24, v26, v27
	v_cvt_pk_bf16_f32 v25, v28, v29
	v_add_u32_e32 v116, 0, v116
	v_cvt_pk_bf16_f32 v26, v102, v103
	v_cvt_pk_bf16_f32 v27, v100, v101
	v_cvt_pk_bf16_f32 v28, v106, v107
	v_cvt_pk_bf16_f32 v29, v104, v105
	v_cvt_pk_bf16_f32 v30, v88, v89
	v_cvt_pk_bf16_f32 v31, v94, v95
	v_cvt_pk_bf16_f32 v32, v98, v99
	v_cvt_pk_bf16_f32 v33, v96, v97
	v_cvt_pk_bf16_f32 v34, v86, v87
	v_cvt_pk_bf16_f32 v35, v84, v85
	v_cvt_pk_bf16_f32 v36, v92, v93
	v_cvt_pk_bf16_f32 v37, v90, v91
	v_cvt_pk_bf16_f32 v38, v72, v73
	v_cvt_pk_bf16_f32 v39, v78, v79
	v_cvt_pk_bf16_f32 v40, v82, v83
	v_cvt_pk_bf16_f32 v41, v80, v81
	v_cvt_pk_bf16_f32 v43, v68, v69
	v_cvt_pk_bf16_f32 v44, v76, v77
	v_cvt_pk_bf16_f32 v45, v74, v75
	v_cvt_pk_bf16_f32 v46, v46, v47
	v_cvt_pk_bf16_f32 v47, v48, v49
	v_cvt_pk_bf16_f32 v48, v66, v67
	v_cvt_pk_bf16_f32 v49, v64, v65
	v_cvt_pk_bf16_f32 v52, v62, v63
	s_mov_b32 s54, 0
	v_lshl_add_u64 v[60:61], v[60:61], 0, v[122:123]
	s_add_i32 s55, s55, 32
	v_fmamk_f32 v71, v109, 0x80000000, v70
	v_fmac_f32_e32 v70, 0, v109
	v_mov_b32_e32 v57, v56
	v_mov_b32_e32 v59, v58
	v_add_u32_e32 v72, s2, v111
	v_mov_b32_e32 v66, v1
	v_mov_b32_e32 v67, v1
	v_mov_b32_e32 v63, 0
	s_movk_i32 s58, 0xfc00
	v_add_u32_e32 v73, 0, v119
	v_add_u32_e32 v74, 0, v120
	v_add_u32_e32 v75, 0, v118
	v_lshlrev_b32_e32 v62, 1, v108
	v_lshlrev_b32_e32 v64, 1, v54
	v_add_u32_e32 v76, 0, v117
	s_mov_b32 s68, 0
	v_mov_b32_e32 v92, 0
	v_mov_b32_e32 v91, 0
	v_mov_b32_e32 v65, 0
	s_mov_b32 s69, 0
	s_waitcnt vmcnt(0)
	v_mov_b32_e32 v140, v112
	v_mov_b32_e32 v141, v113
	v_mov_b32_e32 v142, v114
	v_mov_b32_e32 v143, v115
	s_branch .LBB0_879
.LBB0_877:
	s_or_b64 exec, exec, s[42:43]
	v_or_b32_e32 v63, s2, v111
	v_mov_b64_e32 v[68:69], s[22:23]
	v_mad_i64_i32 v[92:93], s[24:25], v63, s48, v[68:69]
	v_lshl_add_u64 v[92:93], v[92:93], 0, v[0:1]
	v_mov_b32_e32 v65, v1
	v_lshl_add_u64 v[92:93], v[92:93], 0, v[64:65]
	v_add_co_u32_e32 v92, vcc, 0x2000, v92
	v_or_b32_e32 v91, 1, v63
	s_nop 0
	v_addc_co_u32_e32 v93, vcc, 0, v93, vcc
	global_load_ushort v140, v[92:93], off
	v_mad_i64_i32 v[92:93], s[24:25], v91, s48, v[68:69]
	v_lshl_add_u64 v[92:93], v[92:93], 0, v[0:1]
	v_lshl_add_u64 v[92:93], v[92:93], 0, v[64:65]
	v_add_co_u32_e32 v92, vcc, 0x2000, v92
	v_or_b32_e32 v91, 2, v63
	s_nop 0
	v_addc_co_u32_e32 v93, vcc, 0, v93, vcc
	global_load_ushort v141, v[92:93], off
	v_mad_i64_i32 v[92:93], s[24:25], v91, s48, v[68:69]
	v_lshl_add_u64 v[92:93], v[92:93], 0, v[0:1]
	v_or_b32_e32 v63, 3, v63
	v_lshl_add_u64 v[92:93], v[92:93], 0, v[64:65]
	v_mad_i64_i32 v[68:69], s[24:25], v63, s48, v[68:69]
	v_add_co_u32_e32 v92, vcc, 0x2000, v92
	v_lshl_add_u64 v[68:69], v[68:69], 0, v[0:1]
	s_nop 0
	v_addc_co_u32_e32 v93, vcc, 0, v93, vcc
	v_lshl_add_u64 v[68:69], v[68:69], 0, v[64:65]
	v_add_co_u32_e32 v68, vcc, 0x2000, v68
	global_load_ushort v142, v[92:93], off
	s_nop 0
	v_addc_co_u32_e32 v69, vcc, 0, v69, vcc
	global_load_ushort v143, v[68:69], off
	s_waitcnt lgkmcnt(0)
	ds_read2st64_b32 v[124:125], v76 offset1:1
	ds_read2_b32 v[126:127], v76 offset0:132 offset1:196
	ds_read2st64_b32 v[128:129], v90 offset0:4 offset1:5
	ds_read2st64_b32 v[130:131], v89 offset0:6 offset1:7
	ds_read2st64_b32 v[132:133], v88 offset0:8 offset1:9
	ds_read2st64_b32 v[134:135], v87 offset0:10 offset1:11
	ds_read2st64_b32 v[136:137], v86 offset0:12 offset1:13
	ds_read2st64_b32 v[138:139], v85 offset0:14 offset1:15
	s_and_b32 s2, s68, 2
	s_add_i32 s2, s2, s96
	v_mov_b32_e32 v92, v114
	s_waitcnt lgkmcnt(7)
	v_add_f32_e32 v63, v71, v124
	v_add_f32_e32 v65, v70, v125
	ds_read2st64_b32 v[124:125], v84 offset0:16 offset1:17
	v_mul_f32_e32 v91, v109, v65
	v_mul_f32_e32 v65, v55, v65
	v_fma_f32 v91, v55, v63, -v91
	v_fmac_f32_e32 v65, v109, v63
	s_waitcnt lgkmcnt(7)
	v_add_f32_e32 v91, v126, v91
	v_add_f32_e32 v63, v127, v65
	ds_read2st64_b32 v[126:127], v83 offset0:18 offset1:19
	v_mul_f32_e32 v65, v109, v63
	v_mul_f32_e32 v63, v55, v63
	v_fma_f32 v65, v55, v91, -v65
	v_fmac_f32_e32 v63, v109, v91
	s_waitcnt lgkmcnt(7)
	v_add_f32_e32 v65, v128, v65
	v_add_f32_e32 v63, v129, v63
	ds_read2st64_b32 v[128:129], v82 offset0:20 offset1:21
	v_mul_f32_e32 v89, v109, v63
	v_mul_f32_e32 v63, v55, v63
	v_fma_f32 v89, v55, v65, -v89
	v_fmac_f32_e32 v63, v109, v65
	s_waitcnt lgkmcnt(7)
	v_add_f32_e32 v89, v130, v89
	v_add_f32_e32 v63, v131, v63
	ds_read2st64_b32 v[130:131], v81 offset0:22 offset1:23
	v_mul_f32_e32 v65, v109, v63
	v_mul_f32_e32 v63, v55, v63
	v_fma_f32 v65, v55, v89, -v65
	v_fmac_f32_e32 v63, v109, v89
	s_waitcnt lgkmcnt(7)
	v_add_f32_e32 v65, v132, v65
	v_add_f32_e32 v63, v133, v63
	ds_read2st64_b32 v[132:133], v80 offset0:24 offset1:25
	v_mul_f32_e32 v87, v109, v63
	v_mul_f32_e32 v63, v55, v63
	v_fma_f32 v87, v55, v65, -v87
	v_fmac_f32_e32 v63, v109, v65
	s_waitcnt lgkmcnt(7)
	v_add_f32_e32 v87, v134, v87
	v_add_f32_e32 v63, v135, v63
	ds_read2st64_b32 v[134:135], v79 offset0:26 offset1:27
	v_mul_f32_e32 v65, v109, v63
	v_mul_f32_e32 v63, v55, v63
	v_fma_f32 v65, v55, v87, -v65
	v_fmac_f32_e32 v63, v109, v87
	s_waitcnt lgkmcnt(7)
	v_add_f32_e32 v65, v136, v65
	v_add_f32_e32 v63, v137, v63
	ds_read2st64_b32 v[136:137], v78 offset0:28 offset1:29
	v_mul_f32_e32 v85, v109, v63
	v_mul_f32_e32 v63, v55, v63
	v_fma_f32 v85, v55, v65, -v85
	v_fmac_f32_e32 v63, v109, v65
	s_waitcnt lgkmcnt(7)
	v_add_f32_e32 v85, v138, v85
	v_add_f32_e32 v63, v139, v63
	ds_read2st64_b32 v[138:139], v77 offset0:30 offset1:31
	v_mul_f32_e32 v65, v109, v63
	v_mul_f32_e32 v63, v55, v63
	v_fma_f32 v65, v55, v85, -v65
	v_fmac_f32_e32 v63, v109, v85
	s_waitcnt lgkmcnt(7)
	v_add_f32_e32 v65, v124, v65
	v_add_f32_e32 v63, v125, v63
	v_mul_f32_e32 v83, v109, v63
	v_mul_f32_e32 v63, v55, v63
	v_fma_f32 v83, v55, v65, -v83
	v_fmac_f32_e32 v63, v109, v65
	s_waitcnt lgkmcnt(6)
	v_add_f32_e32 v83, v126, v83
	v_add_f32_e32 v63, v127, v63
	v_mul_f32_e32 v65, v109, v63
	v_mul_f32_e32 v63, v55, v63
	v_fma_f32 v65, v55, v83, -v65
	v_fmac_f32_e32 v63, v109, v83
	s_waitcnt lgkmcnt(5)
	v_add_f32_e32 v65, v128, v65
	v_add_f32_e32 v63, v129, v63
	v_mul_f32_e32 v81, v109, v63
	v_mul_f32_e32 v63, v55, v63
	v_fma_f32 v81, v55, v65, -v81
	v_fmac_f32_e32 v63, v109, v65
	s_waitcnt lgkmcnt(4)
	v_add_f32_e32 v81, v130, v81
	v_add_f32_e32 v63, v131, v63
	v_mul_f32_e32 v65, v109, v63
	v_mul_f32_e32 v63, v55, v63
	v_fma_f32 v65, v55, v81, -v65
	v_fmac_f32_e32 v63, v109, v81
	s_waitcnt lgkmcnt(3)
	v_add_f32_e32 v65, v132, v65
	v_add_f32_e32 v63, v133, v63
	v_mul_f32_e32 v79, v109, v63
	v_mul_f32_e32 v63, v55, v63
	v_fma_f32 v79, v55, v65, -v79
	v_fmac_f32_e32 v63, v109, v65
	s_waitcnt lgkmcnt(2)
	v_add_f32_e32 v79, v134, v79
	v_add_f32_e32 v63, v135, v63
	v_mul_f32_e32 v65, v109, v63
	v_mul_f32_e32 v63, v55, v63
	v_fma_f32 v65, v55, v79, -v65
	v_fmac_f32_e32 v63, v109, v79
	s_waitcnt lgkmcnt(1)
	v_add_f32_e32 v65, v136, v65
	v_add_f32_e32 v63, v137, v63
	v_mul_f32_e32 v77, v109, v63
	v_mul_f32_e32 v63, v55, v63
	v_fma_f32 v77, v55, v65, -v77
	v_fmac_f32_e32 v63, v109, v65
	s_waitcnt lgkmcnt(0)
	v_add_f32_e32 v68, v138, v77
	v_add_f32_e32 v63, v139, v63
	v_lshl_add_u32 v65, s2, 9, v116
	ds_write2st64_b32 v65, v68, v63 offset1:1
	v_mov_b32_e32 v65, v112
	v_mov_b32_e32 v91, v113
	v_mov_b32_e32 v63, v115

.LBB0_879:
	s_cmp_eq_u32 s54, 0
	v_add_u32_e32 v90, 32, v76
	v_add_u32_e32 v89, 48, v76
	v_add_u32_e32 v88, 64, v76
	v_add_u32_e32 v87, 0x50, v76
	v_add_u32_e32 v86, 0x60, v76
	v_add_u32_e32 v85, 0x70, v76
	v_add_u32_e32 v84, 0x80, v76
	v_add_u32_e32 v83, 0x90, v76
	v_add_u32_e32 v82, 0xa0, v76
	v_add_u32_e32 v81, 0xb0, v76
	v_add_u32_e32 v80, 0xc0, v76
	v_add_u32_e32 v79, 0xd0, v76
	v_add_u32_e32 v78, 0xe0, v76
	v_add_u32_e32 v77, 0xf0, v76
	s_cbranch_scc1 .LBB0_881
	s_and_b32 s2, s58, 0x400
	v_add_u32_e32 v68, s2, v116
	ds_read2st64_b32 v[94:95], v68 offset1:1
	v_pk_mul_f32 v[96:97], v[58:59], v[66:67]
	v_cndmask_b32_e64 v93, 0, v67, s[88:89]
	v_cndmask_b32_e64 v100, 0, v66, s[88:89]
	v_pk_fma_f32 v[98:99], v[56:57], v[66:67], v[96:97] op_sel:[0,0,1] op_sel_hi:[1,1,0]
	v_pk_fma_f32 v[66:67], v[56:57], v[66:67], v[96:97] op_sel:[0,0,1] op_sel_hi:[1,1,0] neg_lo:[0,0,1] neg_hi:[0,0,1]
	ds_read2st64_b32 v[68:69], v68 offset0:2 offset1:3
	v_mov_b32_e32 v99, v67
	s_waitcnt lgkmcnt(1)
	v_mov_b32_e32 v66, v95
	v_mov_b32_e32 v67, v94
	v_pk_add_f32 v[94:95], v[98:99], v[66:67]
	s_nop 0
	v_pk_mul_f32 v[96:97], v[58:59], v[94:95]
	v_cndmask_b32_e64 v93, v93, v95, s[90:91]
	v_cndmask_b32_e64 v98, v100, v94, s[90:91]
	v_pk_fma_f32 v[66:67], v[56:57], v[94:95], v[96:97] op_sel:[0,0,1] op_sel_hi:[1,1,0]
	v_pk_fma_f32 v[94:95], v[56:57], v[94:95], v[96:97] op_sel:[0,0,1] op_sel_hi:[1,1,0] neg_lo:[0,0,1] neg_hi:[0,0,1]
	v_mul_f32_e32 v96, v109, v98
	v_mov_b32_e32 v67, v95
	ds_read2st64_b32 v[124:125], v76 offset1:1
	ds_read2_b32 v[126:127], v76 offset0:132 offset1:196
	ds_read2st64_b32 v[128:129], v90 offset0:4 offset1:5
	ds_read2st64_b32 v[130:131], v89 offset0:6 offset1:7
	ds_read2st64_b32 v[132:133], v88 offset0:8 offset1:9
	v_fma_f32 v96, v55, v93, -v96
	s_waitcnt lgkmcnt(4)
	v_add_f32_e32 v96, v124, v96
	v_mul_f32_e32 v94, v55, v98
	v_fmac_f32_e32 v94, v109, v93
	v_add_f32_e32 v93, v94, v125
	ds_read2st64_b32 v[124:125], v87 offset0:10 offset1:11
	v_cvt_pk_bf16_f32 v94, v96, s0
	ds_write_b16 v73, v94
	v_cvt_pk_bf16_f32 v94, v93, s0
	ds_write_b16 v73, v94 offset:128
	v_mul_f32_e32 v97, v109, v93
	v_fma_f32 v97, v55, v96, -v97
	v_mul_f32_e32 v93, v55, v93
	v_fmac_f32_e32 v93, v109, v96
	s_waitcnt lgkmcnt(6)
	v_add_f32_e32 v97, v97, v126
	v_add_f32_e32 v93, v93, v127
	ds_read2st64_b32 v[126:127], v86 offset0:12 offset1:13
	v_cvt_pk_bf16_f32 v94, v97, s0
	ds_write_b16 v73, v94 offset:272
	v_cvt_pk_bf16_f32 v94, v93, s0
	ds_write_b16 v73, v94 offset:400
	v_mul_f32_e32 v96, v109, v93
	v_fma_f32 v96, v55, v97, -v96
	v_mul_f32_e32 v93, v55, v93
	v_fmac_f32_e32 v93, v109, v97
	s_waitcnt lgkmcnt(8)
	v_add_f32_e32 v96, v96, v128
	v_add_f32_e32 v93, v93, v129
	ds_read2st64_b32 v[128:129], v85 offset0:14 offset1:15
	v_cvt_pk_bf16_f32 v94, v96, s0
	ds_write_b16 v73, v94 offset:544
	v_cvt_pk_bf16_f32 v94, v93, s0
	ds_write_b16 v73, v94 offset:672
	v_mul_f32_e32 v97, v109, v93
	v_fma_f32 v97, v55, v96, -v97
	v_mul_f32_e32 v93, v55, v93
	v_fmac_f32_e32 v93, v109, v96
	s_waitcnt lgkmcnt(10)
	v_add_f32_e32 v97, v97, v130
	v_add_f32_e32 v93, v93, v131
	ds_read2st64_b32 v[130:131], v84 offset0:16 offset1:17
	v_cvt_pk_bf16_f32 v94, v97, s0
	ds_write_b16 v73, v94 offset:816
	v_cvt_pk_bf16_f32 v94, v93, s0
	ds_write_b16 v73, v94 offset:944
	v_mul_f32_e32 v96, v109, v93
	v_fma_f32 v96, v55, v97, -v96
	v_mul_f32_e32 v93, v55, v93
	v_fmac_f32_e32 v93, v109, v97
	s_waitcnt lgkmcnt(12)
	v_add_f32_e32 v96, v96, v132
	v_add_f32_e32 v93, v93, v133
	ds_read2st64_b32 v[132:133], v83 offset0:18 offset1:19
	v_cvt_pk_bf16_f32 v94, v96, s0
	ds_write_b16 v73, v94 offset:1088
	v_cvt_pk_bf16_f32 v94, v93, s0
	ds_write_b16 v73, v94 offset:1216
	v_mul_f32_e32 v97, v109, v93
	v_fma_f32 v97, v55, v96, -v97
	v_mul_f32_e32 v93, v55, v93
	v_fmac_f32_e32 v93, v109, v96
	s_waitcnt lgkmcnt(14)
	v_add_f32_e32 v97, v97, v124
	v_add_f32_e32 v93, v93, v125
	ds_read2st64_b32 v[124:125], v82 offset0:20 offset1:21
	v_cvt_pk_bf16_f32 v94, v97, s0
	ds_write_b16 v73, v94 offset:1360
	v_cvt_pk_bf16_f32 v94, v93, s0
	ds_write_b16 v73, v94 offset:1488
	v_mul_f32_e32 v96, v109, v93
	v_fma_f32 v96, v55, v97, -v96
	v_mul_f32_e32 v93, v55, v93
	v_fmac_f32_e32 v93, v109, v97
	s_waitcnt lgkmcnt(14)
	v_add_f32_e32 v96, v96, v126
	v_add_f32_e32 v93, v93, v127
	ds_read2st64_b32 v[126:127], v81 offset0:22 offset1:23
	v_cvt_pk_bf16_f32 v94, v96, s0
	ds_write_b16 v73, v94 offset:1632
	v_cvt_pk_bf16_f32 v94, v93, s0
	ds_write_b16 v73, v94 offset:1760
	v_mul_f32_e32 v97, v109, v93
	v_fma_f32 v97, v55, v96, -v97
	v_mul_f32_e32 v93, v55, v93
	v_fmac_f32_e32 v93, v109, v96
	s_waitcnt lgkmcnt(14)
	v_add_f32_e32 v97, v97, v128
	v_add_f32_e32 v93, v93, v129
	ds_read2st64_b32 v[128:129], v80 offset0:24 offset1:25
	v_cvt_pk_bf16_f32 v94, v97, s0
	ds_write_b16 v73, v94 offset:1904
	v_cvt_pk_bf16_f32 v94, v93, s0
	ds_write_b16 v73, v94 offset:2032
	v_mul_f32_e32 v96, v109, v93
	v_fma_f32 v96, v55, v97, -v96
	v_mul_f32_e32 v93, v55, v93
	v_fmac_f32_e32 v93, v109, v97
	s_waitcnt lgkmcnt(14)
	v_add_f32_e32 v96, v96, v130
	v_add_f32_e32 v93, v93, v131
	ds_read2st64_b32 v[130:131], v79 offset0:26 offset1:27
	v_cvt_pk_bf16_f32 v94, v96, s0
	ds_write_b16 v73, v94 offset:2176
	v_cvt_pk_bf16_f32 v94, v93, s0
	ds_write_b16 v73, v94 offset:2304
	v_mul_f32_e32 v97, v109, v93
	v_fma_f32 v97, v55, v96, -v97
	v_mul_f32_e32 v93, v55, v93
	v_fmac_f32_e32 v93, v109, v96
	s_waitcnt lgkmcnt(14)
	v_add_f32_e32 v97, v97, v132
	v_add_f32_e32 v93, v93, v133
	ds_read2st64_b32 v[132:133], v78 offset0:28 offset1:29
	v_cvt_pk_bf16_f32 v94, v97, s0
	ds_write_b16 v73, v94 offset:2448
	v_cvt_pk_bf16_f32 v94, v93, s0
	ds_write_b16 v73, v94 offset:2576
	v_mul_f32_e32 v96, v109, v93
	v_fma_f32 v96, v55, v97, -v96
	v_mul_f32_e32 v93, v55, v93
	v_fmac_f32_e32 v93, v109, v97
	s_waitcnt lgkmcnt(14)
	v_add_f32_e32 v96, v96, v124
	v_add_f32_e32 v93, v93, v125
	ds_read2st64_b32 v[124:125], v77 offset0:30 offset1:31
	v_cvt_pk_bf16_f32 v94, v96, s0
	ds_write_b16 v73, v94 offset:2720
	v_cvt_pk_bf16_f32 v94, v93, s0
	ds_write_b16 v73, v94 offset:2848
	v_mul_f32_e32 v97, v109, v93
	v_fma_f32 v97, v55, v96, -v97
	v_mul_f32_e32 v93, v55, v93
	v_fmac_f32_e32 v93, v109, v96
	s_waitcnt lgkmcnt(14)
	v_add_f32_e32 v97, v97, v126
	v_add_f32_e32 v93, v93, v127
	v_cvt_pk_bf16_f32 v94, v97, s0
	ds_write_b16 v73, v94 offset:2992
	v_cvt_pk_bf16_f32 v94, v93, s0
	ds_write_b16 v73, v94 offset:3120
	v_mul_f32_e32 v96, v109, v93
	v_fma_f32 v96, v55, v97, -v96
	v_mul_f32_e32 v93, v55, v93
	v_fmac_f32_e32 v93, v109, v97
	s_waitcnt lgkmcnt(13)
	v_add_f32_e32 v96, v96, v128
	v_add_f32_e32 v93, v93, v129
	v_cvt_pk_bf16_f32 v94, v96, s0
	ds_write_b16 v73, v94 offset:3264
	v_cvt_pk_bf16_f32 v94, v93, s0
	ds_write_b16 v73, v94 offset:3392
	v_mul_f32_e32 v97, v109, v93
	v_fma_f32 v97, v55, v96, -v97
	v_mul_f32_e32 v93, v55, v93
	v_fmac_f32_e32 v93, v109, v96
	s_waitcnt lgkmcnt(12)
	v_add_f32_e32 v97, v97, v130
	v_add_f32_e32 v93, v93, v131
	v_cvt_pk_bf16_f32 v94, v97, s0
	ds_write_b16 v73, v94 offset:3536
	v_cvt_pk_bf16_f32 v94, v93, s0
	ds_write_b16 v73, v94 offset:3664
	v_mul_f32_e32 v96, v109, v93
	v_fma_f32 v96, v55, v97, -v96
	v_mul_f32_e32 v93, v55, v93
	v_fmac_f32_e32 v93, v109, v97
	s_waitcnt lgkmcnt(11)
	v_add_f32_e32 v96, v96, v132
	v_add_f32_e32 v93, v93, v133
	v_cvt_pk_bf16_f32 v94, v96, s0
	ds_write_b16 v73, v94 offset:3808
	v_cvt_pk_bf16_f32 v94, v93, s0
	ds_write_b16 v73, v94 offset:3936
	v_mul_f32_e32 v97, v109, v93
	v_mul_f32_e32 v93, v55, v93
	v_fma_f32 v97, v55, v96, -v97
	v_fmac_f32_e32 v93, v109, v96
	s_waitcnt lgkmcnt(10)
	v_add_f32_e32 v94, v97, v124
	v_add_f32_e32 v93, v93, v125
	v_cvt_pk_bf16_f32 v94, v94, s0
	v_cvt_pk_bf16_f32 v93, v93, s0
	ds_write_b16 v73, v94 offset:4080
	ds_write_b16 v73, v93 offset:4208
	v_mov_b32_e32 v94, v69
	v_mov_b32_e32 v95, v68
	v_pk_add_f32 v[66:67], v[94:95], v[66:67]
	s_waitcnt lgkmcnt(0)
	ds_read_b128 v[94:97], v74
	ds_read_b128 v[98:101], v74 offset:64
	s_waitcnt lgkmcnt(1)
	v_mfma_f32_16x16x32_bf16 v[94:97], v[94:97], v[10:13], 0
	v_add_u32_e32 v93, s54, v72
	v_add_u32_e32 v68, 0xffffff80, v93
	v_ashrrev_i32_e32 v69, 31, v68
	s_waitcnt lgkmcnt(0)
	v_mfma_f32_16x16x32_bf16 v[94:97], v[98:101], v[14:17], v[94:97]
	ds_read_b128 v[98:101], v74 offset:128
	v_lshlrev_b64 v[68:69], 11, v[68:69]
	v_lshl_add_u64 v[68:69], v[60:61], 0, v[68:69]
	s_waitcnt lgkmcnt(0)
	v_mfma_f32_16x16x32_bf16 v[94:97], v[98:101], v[18:21], v[94:97]
	ds_read_b128 v[98:101], v74 offset:192
	s_waitcnt lgkmcnt(0)
	v_mfma_f32_16x16x32_bf16 v[94:97], v[98:101], v[22:25], v[94:97]
	v_lshlrev_b32_e32 v98, 16, v65
	s_nop 6
	v_fma_f32 v94, v110, v98, v94
	v_mul_f32_e32 v99, 0x3d372713, v94
	v_mul_f32_e32 v99, v94, v99
	v_mul_f32_e32 v98, 0.5, v94
	v_fmac_f32_e32 v94, v94, v99
	v_mul_f32_e32 v94, 0x3f4c422a, v94
	v_add_f32_e32 v94, v94, v94
	v_mul_f32_e32 v94, 0x3fb8aa3b, v94
	v_exp_f32_e32 v94, v94
	s_nop 0
	v_add_f32_e32 v94, 1.0, v94
	v_rcp_f32_e32 v94, v94
	s_nop 0
	v_fma_f32 v94, v94, -2.0, 1.0
	v_add_f32_e32 v94, 1.0, v94
	v_mul_f32_e32 v94, v98, v94
	v_cvt_pk_bf16_f32 v94, v94, s0
	global_store_short v[68:69], v94, off
	v_lshlrev_b32_e32 v94, 16, v91
	v_fma_f32 v94, v110, v94, v95
	v_mul_f32_e32 v98, 0x3d372713, v94
	v_mul_f32_e32 v98, v94, v98
	v_mul_f32_e32 v95, 0.5, v94
	v_fmac_f32_e32 v94, v94, v98
	v_mul_f32_e32 v94, 0x3f4c422a, v94
	v_add_f32_e32 v94, v94, v94
	v_mul_f32_e32 v94, 0x3fb8aa3b, v94
	v_exp_f32_e32 v94, v94
	v_add_u32_e32 v68, 0xffffff81, v93
	v_ashrrev_i32_e32 v69, 31, v68
	v_lshlrev_b64 v[68:69], 11, v[68:69]
	v_add_f32_e32 v94, 1.0, v94
	v_rcp_f32_e32 v94, v94
	v_lshl_add_u64 v[68:69], v[60:61], 0, v[68:69]
	v_fma_f32 v94, v94, -2.0, 1.0
	v_add_f32_e32 v94, 1.0, v94
	v_mul_f32_e32 v94, v95, v94
	v_cvt_pk_bf16_f32 v94, v94, s0
	global_store_short v[68:69], v94, off
	v_lshlrev_b32_e32 v94, 16, v92
	v_fma_f32 v94, v110, v94, v96
	v_mul_f32_e32 v96, 0x3d372713, v94
	v_mul_f32_e32 v96, v94, v96
	v_mul_f32_e32 v95, 0.5, v94
	v_fmac_f32_e32 v94, v94, v96
	v_mul_f32_e32 v94, 0x3f4c422a, v94
	v_add_f32_e32 v94, v94, v94
	v_mul_f32_e32 v94, 0x3fb8aa3b, v94
	v_exp_f32_e32 v94, v94
	v_add_u32_e32 v68, 0xffffff82, v93
	v_ashrrev_i32_e32 v69, 31, v68
	v_lshlrev_b64 v[68:69], 11, v[68:69]
	v_add_f32_e32 v94, 1.0, v94
	v_rcp_f32_e32 v94, v94
	v_lshl_add_u64 v[68:69], v[60:61], 0, v[68:69]
	v_fma_f32 v94, v94, -2.0, 1.0
	v_add_f32_e32 v94, 1.0, v94
	v_mul_f32_e32 v94, v95, v94
	v_cvt_pk_bf16_f32 v94, v94, s0
	global_store_short v[68:69], v94, off
	v_add_u32_e32 v68, 0xffffff83, v93
	v_lshlrev_b32_e32 v93, 16, v63
	v_fmac_f32_e32 v97, v110, v93
	v_mul_f32_e32 v94, 0x3d372713, v97
	v_mul_f32_e32 v94, v97, v94
	v_mul_f32_e32 v93, 0.5, v97
	v_fmac_f32_e32 v97, v97, v94
	v_mul_f32_e32 v94, 0x3f4c422a, v97
	v_add_f32_e32 v94, v94, v94
	v_mul_f32_e32 v94, 0x3fb8aa3b, v94
	v_exp_f32_e32 v94, v94
	v_ashrrev_i32_e32 v69, 31, v68
	v_lshlrev_b64 v[68:69], 11, v[68:69]
	v_lshl_add_u64 v[68:69], v[60:61], 0, v[68:69]
	v_add_f32_e32 v94, 1.0, v94
	v_rcp_f32_e32 v94, v94
	s_nop 0
	v_fma_f32 v94, v94, -2.0, 1.0
	v_add_f32_e32 v94, 1.0, v94
	v_mul_f32_e32 v93, v93, v94
	v_cvt_pk_bf16_f32 v93, v93, s0
	global_store_short v[68:69], v93, off
	s_waitcnt lgkmcnt(0)
.LBB0_881:
	s_cmpk_eq_i32 s54, 0x1000
	s_cbranch_scc1 .LBB0_878
	s_waitcnt vmcnt(4)
	v_mov_b32_e32 v112, v140
	v_mov_b32_e32 v113, v141
	v_mov_b32_e32 v114, v142
	v_mov_b32_e32 v115, v143
	v_mfma_f32_16x16x32_bf16 v[92:95], v[2:5], v[50:53], 0
	v_add_u32_e32 v63, 0x400, v75
	s_min_u32 s2, s69, 0x7e
	s_lshl_b32 s2, s2, 5
	v_mfma_f32_16x16x32_bf16 v[96:99], v[2:5], v[46:49], 0
	s_nop 7
	ds_write2_b32 v75, v92, v96 offset1:16
	ds_write2_b32 v75, v93, v97 offset0:132 offset1:148
	ds_write2_b32 v63, v94, v98 offset0:8 offset1:24
	ds_write2_b32 v63, v95, v99 offset0:140 offset1:156
	v_mfma_f32_16x16x32_bf16 v[92:95], v[2:5], v[42:45], 0
	s_add_i32 s2, s55, s2
	v_mfma_f32_16x16x32_bf16 v[96:99], v[2:5], v[38:41], 0
	s_nop 7
	ds_write2_b32 v75, v92, v96 offset0:32 offset1:48
	ds_write2_b32 v75, v93, v97 offset0:164 offset1:180
	ds_write2_b32 v63, v94, v98 offset0:40 offset1:56
	ds_write2_b32 v63, v95, v99 offset0:172 offset1:188
	v_mfma_f32_16x16x32_bf16 v[92:95], v[2:5], v[34:37], 0
	v_mfma_f32_16x16x32_bf16 v[96:99], v[2:5], v[30:33], 0
	s_nop 7
	ds_write2_b32 v75, v92, v96 offset0:64 offset1:80
	ds_write2_b32 v75, v93, v97 offset0:196 offset1:212
	ds_write2_b32 v63, v94, v98 offset0:72 offset1:88
	ds_write2_b32 v63, v95, v99 offset0:204 offset1:220
	v_mfma_f32_16x16x32_bf16 v[92:95], v[2:5], v[26:29], 0
	v_mfma_f32_16x16x32_bf16 v[96:99], v[2:5], v[6:9], 0
	s_nop 7
	ds_write2_b32 v75, v92, v96 offset0:96 offset1:112
	ds_write2_b32 v75, v93, v97 offset0:228 offset1:244
	ds_write2_b32 v63, v94, v98 offset0:104 offset1:120
	ds_write2_b32 v63, v95, v99 offset0:236 offset1:252
	s_and_saveexec_b64 s[42:43], s[0:1]
	s_cbranch_execz .LBB0_877
	v_or_b32_e32 v4, s2, v54
	v_mov_b64_e32 v[2:3], s[22:23]
	v_mad_i64_i32 v[2:3], s[24:25], v4, s48, v[2:3]
	v_lshl_add_u64 v[2:3], v[2:3], 0, v[0:1]
	v_mov_b32_e32 v63, v1
	v_lshl_add_u64 v[2:3], v[2:3], 0, v[62:63]
	v_add_co_u32_e32 v2, vcc, 0x2000, v2
	s_nop 1
	v_addc_co_u32_e32 v3, vcc, 0, v3, vcc
	global_load_dwordx4 v[2:5], v[2:3], off
	s_branch .LBB0_877

.LBB0_906:
	s_cmp_eq_u32 s0, -1
	s_cbranch_scc1 .LBB0_905
	s_and_b32 s1, s0, 1
	s_mul_i32 s2, s1, 0xa000
	v_or_b32_e32 v0, s2, v10
	s_nop 0
	v_add_u32_e32 v5, 0, v0
	v_lshl_or_b32 v0, s1, 11, v13
	s_nop 0
	v_add_u32_e32 v14, 0, v0
	v_mov_b32_e32 v0, v11
	v_add_u32_e32 v0, 0, v0
	ds_read_b128 v[48:51], v5 offset:24576
	ds_read_b128 v[40:43], v5 offset:8192
	ds_read_b32 v56, v14
	ds_read_b128 v[44:47], v5 offset:16384
	ds_read_b128 v[52:55], v5 offset:32768
	ds_read_b128 v[112:115], v5
	ds_read_b128 v[68:71], v5 offset:24832
	ds_read_b128 v[60:63], v5 offset:8448
	ds_read_b32 v76, v14 offset:64
	ds_read_b128 v[64:67], v5 offset:16640
	ds_read_b128 v[72:75], v5 offset:33024
	ds_read_b128 v[116:119], v5 offset:256
	s_waitcnt lgkmcnt(6)
	v_pk_mul_f32 v[32:33], v[40:41], v[56:57] op_sel_hi:[1,0]
	v_pk_mul_f32 v[34:35], v[42:43], v[56:57] op_sel_hi:[1,0]
	v_pk_mul_f32 v[20:21], v[48:49], v[8:9]
	v_pk_fma_f32 v[20:21], v[6:7], v[50:51], v[20:21]
	ds_read_b128 v[100:103], v5 offset:25088
	ds_read_b128 v[92:95], v5 offset:8704
	ds_read_b32 v108, v14 offset:128
	ds_read_b128 v[96:99], v5 offset:16896
	ds_read_b128 v[104:107], v5 offset:33280
	ds_read_b128 v[120:123], v5 offset:512
	v_add_f32_e32 v15, v20, v21
	v_pk_fma_f32 v[16:17], v[8:9], v[44:45], v[32:33]
	v_pk_fma_f32 v[18:19], v[6:7], v[46:47], v[34:35]
	v_add_f32_dpp v15, v15, v15 quad_perm:[1,0,3,2] row_mask:0xf bank_mask:0xf bound_ctrl:1
	s_nop 1
	v_add_f32_dpp v15, v15, v15 quad_perm:[2,3,0,1] row_mask:0xf bank_mask:0xf bound_ctrl:1
	s_nop 1
	v_add_f32_dpp v15, v15, v15 row_ror:4 row_mask:0xf bank_mask:0xf bound_ctrl:1
	s_waitcnt lgkmcnt(6)
	v_pk_mul_f32 v[36:37], v[60:61], v[76:77] op_sel_hi:[1,0]
	v_pk_mul_f32 v[38:39], v[62:63], v[76:77] op_sel_hi:[1,0]
	v_add_f32_dpp v22, v15, v15 row_ror:8 row_mask:0xf bank_mask:0xf bound_ctrl:1
	v_pk_fma_f32 v[8:9], v[52:53], v[22:23], v[16:17] op_sel_hi:[1,0,1]
	v_pk_fma_f32 v[6:7], v[54:55], v[22:23], v[18:19] op_sel_hi:[1,0,1]
	v_pk_mul_f32 v[20:21], v[68:69], v[8:9]
	v_pk_fma_f32 v[20:21], v[6:7], v[70:71], v[20:21]
	ds_read_b128 v[48:51], v5 offset:25344
	ds_read_b128 v[40:43], v5 offset:8960
	ds_read_b32 v56, v14 offset:192
	ds_read_b128 v[44:47], v5 offset:17152
	ds_read_b128 v[52:55], v5 offset:33536
	ds_read_b128 v[124:127], v5 offset:768
	v_add_f32_e32 v15, v20, v21
	v_pk_fma_f32 v[16:17], v[8:9], v[64:65], v[36:37]
	v_pk_fma_f32 v[18:19], v[6:7], v[66:67], v[38:39]
	v_add_f32_dpp v15, v15, v15 quad_perm:[1,0,3,2] row_mask:0xf bank_mask:0xf bound_ctrl:1
	v_pk_mul_f32 v[24:25], v[112:113], v[8:9]
	v_pk_fma_f32 v[24:25], v[6:7], v[114:115], v[24:25]
	v_add_f32_dpp v15, v15, v15 quad_perm:[2,3,0,1] row_mask:0xf bank_mask:0xf bound_ctrl:1
	v_add_f32_e32 v26, v24, v25
	ds_write_b32 v0, v26
	v_add_f32_dpp v15, v15, v15 row_ror:4 row_mask:0xf bank_mask:0xf bound_ctrl:1
	s_waitcnt lgkmcnt(7)
	v_pk_mul_f32 v[32:33], v[92:93], v[108:109] op_sel_hi:[1,0]
	v_pk_mul_f32 v[34:35], v[94:95], v[108:109] op_sel_hi:[1,0]
	v_add_f32_dpp v22, v15, v15 row_ror:8 row_mask:0xf bank_mask:0xf bound_ctrl:1
	v_pk_fma_f32 v[8:9], v[72:73], v[22:23], v[16:17] op_sel_hi:[1,0,1]
	v_pk_fma_f32 v[6:7], v[74:75], v[22:23], v[18:19] op_sel_hi:[1,0,1]
	v_pk_mul_f32 v[20:21], v[100:101], v[8:9]
	v_pk_fma_f32 v[20:21], v[6:7], v[102:103], v[20:21]
	ds_read_b128 v[68:71], v5 offset:25600
	ds_read_b128 v[60:63], v5 offset:9216
	ds_read_b32 v76, v14 offset:256
	ds_read_b128 v[64:67], v5 offset:17408
	ds_read_b128 v[72:75], v5 offset:33792
	ds_read_b128 v[112:115], v5 offset:1024
	v_add_f32_e32 v15, v20, v21
	v_pk_fma_f32 v[16:17], v[8:9], v[96:97], v[32:33]
	v_pk_fma_f32 v[18:19], v[6:7], v[98:99], v[34:35]
	v_add_f32_dpp v15, v15, v15 quad_perm:[1,0,3,2] row_mask:0xf bank_mask:0xf bound_ctrl:1
	v_pk_mul_f32 v[24:25], v[116:117], v[8:9]
	v_pk_fma_f32 v[24:25], v[6:7], v[118:119], v[24:25]
	v_add_f32_dpp v15, v15, v15 quad_perm:[2,3,0,1] row_mask:0xf bank_mask:0xf bound_ctrl:1
	v_add_f32_e32 v26, v24, v25
	ds_write_b32 v0, v26 offset:256
	v_add_f32_dpp v15, v15, v15 row_ror:4 row_mask:0xf bank_mask:0xf bound_ctrl:1
	s_waitcnt lgkmcnt(8)
	v_pk_mul_f32 v[36:37], v[40:41], v[56:57] op_sel_hi:[1,0]
	v_pk_mul_f32 v[38:39], v[42:43], v[56:57] op_sel_hi:[1,0]
	v_add_f32_dpp v22, v15, v15 row_ror:8 row_mask:0xf bank_mask:0xf bound_ctrl:1
	v_pk_fma_f32 v[8:9], v[104:105], v[22:23], v[16:17] op_sel_hi:[1,0,1]
	v_pk_fma_f32 v[6:7], v[106:107], v[22:23], v[18:19] op_sel_hi:[1,0,1]
	v_pk_mul_f32 v[20:21], v[48:49], v[8:9]
	v_pk_fma_f32 v[20:21], v[6:7], v[50:51], v[20:21]
	ds_read_b128 v[100:103], v5 offset:25856
	ds_read_b128 v[92:95], v5 offset:9472
	ds_read_b32 v108, v14 offset:320
	ds_read_b128 v[96:99], v5 offset:17664
	ds_read_b128 v[104:107], v5 offset:34048
	ds_read_b128 v[116:119], v5 offset:1280
	v_add_f32_e32 v15, v20, v21
	v_pk_fma_f32 v[16:17], v[8:9], v[44:45], v[36:37]
	v_pk_fma_f32 v[18:19], v[6:7], v[46:47], v[38:39]
	v_add_f32_dpp v15, v15, v15 quad_perm:[1,0,3,2] row_mask:0xf bank_mask:0xf bound_ctrl:1
	v_pk_mul_f32 v[24:25], v[120:121], v[8:9]
	v_pk_fma_f32 v[24:25], v[6:7], v[122:123], v[24:25]
	v_add_f32_dpp v15, v15, v15 quad_perm:[2,3,0,1] row_mask:0xf bank_mask:0xf bound_ctrl:1
	v_add_f32_e32 v26, v24, v25
	ds_write_b32 v0, v26 offset:512
	v_add_f32_dpp v15, v15, v15 row_ror:4 row_mask:0xf bank_mask:0xf bound_ctrl:1
	s_waitcnt lgkmcnt(8)
	v_pk_mul_f32 v[32:33], v[60:61], v[76:77] op_sel_hi:[1,0]
	v_pk_mul_f32 v[34:35], v[62:63], v[76:77] op_sel_hi:[1,0]
	v_add_f32_dpp v22, v15, v15 row_ror:8 row_mask:0xf bank_mask:0xf bound_ctrl:1
	v_pk_fma_f32 v[8:9], v[52:53], v[22:23], v[16:17] op_sel_hi:[1,0,1]
	v_pk_fma_f32 v[6:7], v[54:55], v[22:23], v[18:19] op_sel_hi:[1,0,1]
	v_pk_mul_f32 v[20:21], v[68:69], v[8:9]
	v_pk_fma_f32 v[20:21], v[6:7], v[70:71], v[20:21]
	ds_read_b128 v[48:51], v5 offset:26112
	ds_read_b128 v[40:43], v5 offset:9728
	ds_read_b32 v56, v14 offset:384
	ds_read_b128 v[44:47], v5 offset:17920
	ds_read_b128 v[52:55], v5 offset:34304
	ds_read_b128 v[120:123], v5 offset:1536
	v_add_f32_e32 v15, v20, v21
	v_pk_fma_f32 v[16:17], v[8:9], v[64:65], v[32:33]
	v_pk_fma_f32 v[18:19], v[6:7], v[66:67], v[34:35]
	v_add_f32_dpp v15, v15, v15 quad_perm:[1,0,3,2] row_mask:0xf bank_mask:0xf bound_ctrl:1
	v_pk_mul_f32 v[24:25], v[124:125], v[8:9]
	v_pk_fma_f32 v[24:25], v[6:7], v[126:127], v[24:25]
	v_add_f32_dpp v15, v15, v15 quad_perm:[2,3,0,1] row_mask:0xf bank_mask:0xf bound_ctrl:1
	v_add_f32_e32 v26, v24, v25
	ds_write_b32 v0, v26 offset:768
	v_add_f32_dpp v15, v15, v15 row_ror:4 row_mask:0xf bank_mask:0xf bound_ctrl:1
	s_waitcnt lgkmcnt(8)
	v_pk_mul_f32 v[36:37], v[92:93], v[108:109] op_sel_hi:[1,0]
	v_pk_mul_f32 v[38:39], v[94:95], v[108:109] op_sel_hi:[1,0]
	v_add_f32_dpp v22, v15, v15 row_ror:8 row_mask:0xf bank_mask:0xf bound_ctrl:1
	v_pk_fma_f32 v[8:9], v[72:73], v[22:23], v[16:17] op_sel_hi:[1,0,1]
	v_pk_fma_f32 v[6:7], v[74:75], v[22:23], v[18:19] op_sel_hi:[1,0,1]
	v_pk_mul_f32 v[20:21], v[100:101], v[8:9]
	v_pk_fma_f32 v[20:21], v[6:7], v[102:103], v[20:21]
	ds_read_b128 v[68:71], v5 offset:26368
	ds_read_b128 v[60:63], v5 offset:9984
	ds_read_b32 v76, v14 offset:448
	ds_read_b128 v[64:67], v5 offset:18176
	ds_read_b128 v[72:75], v5 offset:34560
	ds_read_b128 v[124:127], v5 offset:1792
	v_add_f32_e32 v15, v20, v21
	v_pk_fma_f32 v[16:17], v[8:9], v[96:97], v[36:37]
	v_pk_fma_f32 v[18:19], v[6:7], v[98:99], v[38:39]
	v_add_f32_dpp v15, v15, v15 quad_perm:[1,0,3,2] row_mask:0xf bank_mask:0xf bound_ctrl:1
	v_pk_mul_f32 v[24:25], v[112:113], v[8:9]
	v_pk_fma_f32 v[24:25], v[6:7], v[114:115], v[24:25]
	v_add_f32_dpp v15, v15, v15 quad_perm:[2,3,0,1] row_mask:0xf bank_mask:0xf bound_ctrl:1
	v_add_f32_e32 v26, v24, v25
	ds_write_b32 v0, v26 offset:1024
	v_add_f32_dpp v15, v15, v15 row_ror:4 row_mask:0xf bank_mask:0xf bound_ctrl:1
	s_waitcnt lgkmcnt(8)
	v_pk_mul_f32 v[32:33], v[40:41], v[56:57] op_sel_hi:[1,0]
	v_pk_mul_f32 v[34:35], v[42:43], v[56:57] op_sel_hi:[1,0]
	v_add_f32_dpp v22, v15, v15 row_ror:8 row_mask:0xf bank_mask:0xf bound_ctrl:1
	v_pk_fma_f32 v[8:9], v[104:105], v[22:23], v[16:17] op_sel_hi:[1,0,1]
	v_pk_fma_f32 v[6:7], v[106:107], v[22:23], v[18:19] op_sel_hi:[1,0,1]
	v_pk_mul_f32 v[20:21], v[48:49], v[8:9]
	v_pk_fma_f32 v[20:21], v[6:7], v[50:51], v[20:21]
	ds_read_b128 v[100:103], v5 offset:26624
	ds_read_b128 v[92:95], v5 offset:10240
	ds_read_b32 v108, v14 offset:512
	ds_read_b128 v[96:99], v5 offset:18432
	ds_read_b128 v[104:107], v5 offset:34816
	ds_read_b128 v[112:115], v5 offset:2048
	v_add_f32_e32 v15, v20, v21
	v_pk_fma_f32 v[16:17], v[8:9], v[44:45], v[32:33]
	v_pk_fma_f32 v[18:19], v[6:7], v[46:47], v[34:35]
	v_add_f32_dpp v15, v15, v15 quad_perm:[1,0,3,2] row_mask:0xf bank_mask:0xf bound_ctrl:1
	v_pk_mul_f32 v[24:25], v[116:117], v[8:9]
	v_pk_fma_f32 v[24:25], v[6:7], v[118:119], v[24:25]
	v_add_f32_dpp v15, v15, v15 quad_perm:[2,3,0,1] row_mask:0xf bank_mask:0xf bound_ctrl:1
	v_add_f32_e32 v26, v24, v25
	ds_write_b32 v0, v26 offset:1280
	v_add_f32_dpp v15, v15, v15 row_ror:4 row_mask:0xf bank_mask:0xf bound_ctrl:1
	s_waitcnt lgkmcnt(8)
	v_pk_mul_f32 v[36:37], v[60:61], v[76:77] op_sel_hi:[1,0]
	v_pk_mul_f32 v[38:39], v[62:63], v[76:77] op_sel_hi:[1,0]
	v_add_f32_dpp v22, v15, v15 row_ror:8 row_mask:0xf bank_mask:0xf bound_ctrl:1
	v_pk_fma_f32 v[8:9], v[52:53], v[22:23], v[16:17] op_sel_hi:[1,0,1]
	v_pk_fma_f32 v[6:7], v[54:55], v[22:23], v[18:19] op_sel_hi:[1,0,1]
	v_pk_mul_f32 v[20:21], v[68:69], v[8:9]
	v_pk_fma_f32 v[20:21], v[6:7], v[70:71], v[20:21]
	ds_read_b128 v[48:51], v5 offset:26880
	ds_read_b128 v[40:43], v5 offset:10496
	ds_read_b32 v56, v14 offset:576
	ds_read_b128 v[44:47], v5 offset:18688
	ds_read_b128 v[52:55], v5 offset:35072
	ds_read_b128 v[116:119], v5 offset:2304
	v_add_f32_e32 v15, v20, v21
	v_pk_fma_f32 v[16:17], v[8:9], v[64:65], v[36:37]
	v_pk_fma_f32 v[18:19], v[6:7], v[66:67], v[38:39]
	v_add_f32_dpp v15, v15, v15 quad_perm:[1,0,3,2] row_mask:0xf bank_mask:0xf bound_ctrl:1
	v_pk_mul_f32 v[24:25], v[120:121], v[8:9]
	v_pk_fma_f32 v[24:25], v[6:7], v[122:123], v[24:25]
	v_add_f32_dpp v15, v15, v15 quad_perm:[2,3,0,1] row_mask:0xf bank_mask:0xf bound_ctrl:1
	v_add_f32_e32 v26, v24, v25
	ds_write_b32 v0, v26 offset:1536
	v_add_f32_dpp v15, v15, v15 row_ror:4 row_mask:0xf bank_mask:0xf bound_ctrl:1
	s_waitcnt lgkmcnt(8)
	v_pk_mul_f32 v[32:33], v[92:93], v[108:109] op_sel_hi:[1,0]
	v_pk_mul_f32 v[34:35], v[94:95], v[108:109] op_sel_hi:[1,0]
	v_add_f32_dpp v22, v15, v15 row_ror:8 row_mask:0xf bank_mask:0xf bound_ctrl:1
	v_pk_fma_f32 v[8:9], v[72:73], v[22:23], v[16:17] op_sel_hi:[1,0,1]
	v_pk_fma_f32 v[6:7], v[74:75], v[22:23], v[18:19] op_sel_hi:[1,0,1]
	v_pk_mul_f32 v[20:21], v[100:101], v[8:9]
	v_pk_fma_f32 v[20:21], v[6:7], v[102:103], v[20:21]
	ds_read_b128 v[68:71], v5 offset:27136
	ds_read_b128 v[60:63], v5 offset:10752
	ds_read_b32 v76, v14 offset:640
	ds_read_b128 v[64:67], v5 offset:18944
	ds_read_b128 v[72:75], v5 offset:35328
	ds_read_b128 v[120:123], v5 offset:2560
	v_add_f32_e32 v15, v20, v21
	v_pk_fma_f32 v[16:17], v[8:9], v[96:97], v[32:33]
	v_pk_fma_f32 v[18:19], v[6:7], v[98:99], v[34:35]
	v_add_f32_dpp v15, v15, v15 quad_perm:[1,0,3,2] row_mask:0xf bank_mask:0xf bound_ctrl:1
	v_pk_mul_f32 v[24:25], v[124:125], v[8:9]
	v_pk_fma_f32 v[24:25], v[6:7], v[126:127], v[24:25]
	v_add_f32_dpp v15, v15, v15 quad_perm:[2,3,0,1] row_mask:0xf bank_mask:0xf bound_ctrl:1
	v_add_f32_e32 v26, v24, v25
	ds_write_b32 v0, v26 offset:1792
	v_add_f32_dpp v15, v15, v15 row_ror:4 row_mask:0xf bank_mask:0xf bound_ctrl:1
	s_waitcnt lgkmcnt(8)
	v_pk_mul_f32 v[36:37], v[40:41], v[56:57] op_sel_hi:[1,0]
	v_pk_mul_f32 v[38:39], v[42:43], v[56:57] op_sel_hi:[1,0]
	v_add_f32_dpp v22, v15, v15 row_ror:8 row_mask:0xf bank_mask:0xf bound_ctrl:1
	v_pk_fma_f32 v[8:9], v[104:105], v[22:23], v[16:17] op_sel_hi:[1,0,1]
	v_pk_fma_f32 v[6:7], v[106:107], v[22:23], v[18:19] op_sel_hi:[1,0,1]
	v_pk_mul_f32 v[20:21], v[48:49], v[8:9]
	v_pk_fma_f32 v[20:21], v[6:7], v[50:51], v[20:21]
	ds_read_b128 v[100:103], v5 offset:27392
	ds_read_b128 v[92:95], v5 offset:11008
	ds_read_b32 v108, v14 offset:704
	ds_read_b128 v[96:99], v5 offset:19200
	ds_read_b128 v[104:107], v5 offset:35584
	ds_read_b128 v[124:127], v5 offset:2816
	v_add_f32_e32 v15, v20, v21
	v_pk_fma_f32 v[16:17], v[8:9], v[44:45], v[36:37]
	v_pk_fma_f32 v[18:19], v[6:7], v[46:47], v[38:39]
	v_add_f32_dpp v15, v15, v15 quad_perm:[1,0,3,2] row_mask:0xf bank_mask:0xf bound_ctrl:1
	v_pk_mul_f32 v[24:25], v[112:113], v[8:9]
	v_pk_fma_f32 v[24:25], v[6:7], v[114:115], v[24:25]
	v_add_f32_dpp v15, v15, v15 quad_perm:[2,3,0,1] row_mask:0xf bank_mask:0xf bound_ctrl:1
	v_add_f32_e32 v26, v24, v25
	ds_write_b32 v0, v26 offset:2048
	v_add_f32_dpp v15, v15, v15 row_ror:4 row_mask:0xf bank_mask:0xf bound_ctrl:1
	s_waitcnt lgkmcnt(8)
	v_pk_mul_f32 v[32:33], v[60:61], v[76:77] op_sel_hi:[1,0]
	v_pk_mul_f32 v[34:35], v[62:63], v[76:77] op_sel_hi:[1,0]
	v_add_f32_dpp v22, v15, v15 row_ror:8 row_mask:0xf bank_mask:0xf bound_ctrl:1
	v_pk_fma_f32 v[8:9], v[52:53], v[22:23], v[16:17] op_sel_hi:[1,0,1]
	v_pk_fma_f32 v[6:7], v[54:55], v[22:23], v[18:19] op_sel_hi:[1,0,1]
	v_pk_mul_f32 v[20:21], v[68:69], v[8:9]
	v_pk_fma_f32 v[20:21], v[6:7], v[70:71], v[20:21]
	ds_read_b128 v[48:51], v5 offset:27648
	ds_read_b128 v[40:43], v5 offset:11264
	ds_read_b32 v56, v14 offset:768
	ds_read_b128 v[44:47], v5 offset:19456
	ds_read_b128 v[52:55], v5 offset:35840
	ds_read_b128 v[112:115], v5 offset:3072
	v_add_f32_e32 v15, v20, v21
	v_pk_fma_f32 v[16:17], v[8:9], v[64:65], v[32:33]
	v_pk_fma_f32 v[18:19], v[6:7], v[66:67], v[34:35]
	v_add_f32_dpp v15, v15, v15 quad_perm:[1,0,3,2] row_mask:0xf bank_mask:0xf bound_ctrl:1
	v_pk_mul_f32 v[24:25], v[116:117], v[8:9]
	v_pk_fma_f32 v[24:25], v[6:7], v[118:119], v[24:25]
	v_add_f32_dpp v15, v15, v15 quad_perm:[2,3,0,1] row_mask:0xf bank_mask:0xf bound_ctrl:1
	v_add_f32_e32 v26, v24, v25
	ds_write_b32 v0, v26 offset:2304
	v_add_f32_dpp v15, v15, v15 row_ror:4 row_mask:0xf bank_mask:0xf bound_ctrl:1
	s_waitcnt lgkmcnt(8)
	v_pk_mul_f32 v[36:37], v[92:93], v[108:109] op_sel_hi:[1,0]
	v_pk_mul_f32 v[38:39], v[94:95], v[108:109] op_sel_hi:[1,0]
	v_add_f32_dpp v22, v15, v15 row_ror:8 row_mask:0xf bank_mask:0xf bound_ctrl:1
	v_pk_fma_f32 v[8:9], v[72:73], v[22:23], v[16:17] op_sel_hi:[1,0,1]
	v_pk_fma_f32 v[6:7], v[74:75], v[22:23], v[18:19] op_sel_hi:[1,0,1]
	v_pk_mul_f32 v[20:21], v[100:101], v[8:9]
	v_pk_fma_f32 v[20:21], v[6:7], v[102:103], v[20:21]
	ds_read_b128 v[68:71], v5 offset:27904
	ds_read_b128 v[60:63], v5 offset:11520
	ds_read_b32 v76, v14 offset:832
	ds_read_b128 v[64:67], v5 offset:19712
	ds_read_b128 v[72:75], v5 offset:36096
	ds_read_b128 v[116:119], v5 offset:3328
	v_add_f32_e32 v15, v20, v21
	v_pk_fma_f32 v[16:17], v[8:9], v[96:97], v[36:37]
	v_pk_fma_f32 v[18:19], v[6:7], v[98:99], v[38:39]
	v_add_f32_dpp v15, v15, v15 quad_perm:[1,0,3,2] row_mask:0xf bank_mask:0xf bound_ctrl:1
	v_pk_mul_f32 v[24:25], v[120:121], v[8:9]
	v_pk_fma_f32 v[24:25], v[6:7], v[122:123], v[24:25]
	v_add_f32_dpp v15, v15, v15 quad_perm:[2,3,0,1] row_mask:0xf bank_mask:0xf bound_ctrl:1
	v_add_f32_e32 v26, v24, v25
	ds_write_b32 v0, v26 offset:2560
	v_add_f32_dpp v15, v15, v15 row_ror:4 row_mask:0xf bank_mask:0xf bound_ctrl:1
	s_waitcnt lgkmcnt(8)
	v_pk_mul_f32 v[32:33], v[40:41], v[56:57] op_sel_hi:[1,0]
	v_pk_mul_f32 v[34:35], v[42:43], v[56:57] op_sel_hi:[1,0]
	v_add_f32_dpp v22, v15, v15 row_ror:8 row_mask:0xf bank_mask:0xf bound_ctrl:1
	v_pk_fma_f32 v[8:9], v[104:105], v[22:23], v[16:17] op_sel_hi:[1,0,1]
	v_pk_fma_f32 v[6:7], v[106:107], v[22:23], v[18:19] op_sel_hi:[1,0,1]
	v_pk_mul_f32 v[20:21], v[48:49], v[8:9]
	v_pk_fma_f32 v[20:21], v[6:7], v[50:51], v[20:21]
	ds_read_b128 v[100:103], v5 offset:28160
	ds_read_b128 v[92:95], v5 offset:11776
	ds_read_b32 v108, v14 offset:896
	ds_read_b128 v[96:99], v5 offset:19968
	ds_read_b128 v[104:107], v5 offset:36352
	ds_read_b128 v[120:123], v5 offset:3584
	v_add_f32_e32 v15, v20, v21
	v_pk_fma_f32 v[16:17], v[8:9], v[44:45], v[32:33]
	v_pk_fma_f32 v[18:19], v[6:7], v[46:47], v[34:35]
	v_add_f32_dpp v15, v15, v15 quad_perm:[1,0,3,2] row_mask:0xf bank_mask:0xf bound_ctrl:1
	v_pk_mul_f32 v[24:25], v[124:125], v[8:9]
	v_pk_fma_f32 v[24:25], v[6:7], v[126:127], v[24:25]
	v_add_f32_dpp v15, v15, v15 quad_perm:[2,3,0,1] row_mask:0xf bank_mask:0xf bound_ctrl:1
	v_add_f32_e32 v26, v24, v25
	ds_write_b32 v0, v26 offset:2816
	v_add_f32_dpp v15, v15, v15 row_ror:4 row_mask:0xf bank_mask:0xf bound_ctrl:1
	s_waitcnt lgkmcnt(8)
	v_pk_mul_f32 v[36:37], v[60:61], v[76:77] op_sel_hi:[1,0]
	v_pk_mul_f32 v[38:39], v[62:63], v[76:77] op_sel_hi:[1,0]
	v_add_f32_dpp v22, v15, v15 row_ror:8 row_mask:0xf bank_mask:0xf bound_ctrl:1
	v_pk_fma_f32 v[8:9], v[52:53], v[22:23], v[16:17] op_sel_hi:[1,0,1]
	v_pk_fma_f32 v[6:7], v[54:55], v[22:23], v[18:19] op_sel_hi:[1,0,1]
	v_pk_mul_f32 v[20:21], v[68:69], v[8:9]
	v_pk_fma_f32 v[20:21], v[6:7], v[70:71], v[20:21]
	ds_read_b128 v[48:51], v5 offset:28416
	ds_read_b128 v[40:43], v5 offset:12032
	ds_read_b32 v56, v14 offset:960
	ds_read_b128 v[44:47], v5 offset:20224
	ds_read_b128 v[52:55], v5 offset:36608
	ds_read_b128 v[124:127], v5 offset:3840
	v_add_f32_e32 v15, v20, v21
	v_pk_fma_f32 v[16:17], v[8:9], v[64:65], v[36:37]
	v_pk_fma_f32 v[18:19], v[6:7], v[66:67], v[38:39]
	v_add_f32_dpp v15, v15, v15 quad_perm:[1,0,3,2] row_mask:0xf bank_mask:0xf bound_ctrl:1
	v_pk_mul_f32 v[24:25], v[112:113], v[8:9]
	v_pk_fma_f32 v[24:25], v[6:7], v[114:115], v[24:25]
	v_add_f32_dpp v15, v15, v15 quad_perm:[2,3,0,1] row_mask:0xf bank_mask:0xf bound_ctrl:1
	v_add_f32_e32 v26, v24, v25
	ds_write_b32 v0, v26 offset:3072
	v_add_f32_dpp v15, v15, v15 row_ror:4 row_mask:0xf bank_mask:0xf bound_ctrl:1
	s_waitcnt lgkmcnt(8)
	v_pk_mul_f32 v[32:33], v[92:93], v[108:109] op_sel_hi:[1,0]
	v_pk_mul_f32 v[34:35], v[94:95], v[108:109] op_sel_hi:[1,0]
	v_add_f32_dpp v22, v15, v15 row_ror:8 row_mask:0xf bank_mask:0xf bound_ctrl:1
	v_pk_fma_f32 v[8:9], v[72:73], v[22:23], v[16:17] op_sel_hi:[1,0,1]
	v_pk_fma_f32 v[6:7], v[74:75], v[22:23], v[18:19] op_sel_hi:[1,0,1]
	v_pk_mul_f32 v[20:21], v[100:101], v[8:9]
	v_pk_fma_f32 v[20:21], v[6:7], v[102:103], v[20:21]
	ds_read_b128 v[68:71], v5 offset:28672
	ds_read_b128 v[60:63], v5 offset:12288
	ds_read_b32 v76, v14 offset:1024
	ds_read_b128 v[64:67], v5 offset:20480
	ds_read_b128 v[72:75], v5 offset:36864
	ds_read_b128 v[112:115], v5 offset:4096
	v_add_f32_e32 v15, v20, v21
	v_pk_fma_f32 v[16:17], v[8:9], v[96:97], v[32:33]
	v_pk_fma_f32 v[18:19], v[6:7], v[98:99], v[34:35]
	v_add_f32_dpp v15, v15, v15 quad_perm:[1,0,3,2] row_mask:0xf bank_mask:0xf bound_ctrl:1
	v_pk_mul_f32 v[24:25], v[116:117], v[8:9]
	v_pk_fma_f32 v[24:25], v[6:7], v[118:119], v[24:25]
	v_add_f32_dpp v15, v15, v15 quad_perm:[2,3,0,1] row_mask:0xf bank_mask:0xf bound_ctrl:1
	v_add_f32_e32 v26, v24, v25
	ds_write_b32 v0, v26 offset:3328
	v_add_f32_dpp v15, v15, v15 row_ror:4 row_mask:0xf bank_mask:0xf bound_ctrl:1
	s_waitcnt lgkmcnt(8)
	v_pk_mul_f32 v[36:37], v[40:41], v[56:57] op_sel_hi:[1,0]
	v_pk_mul_f32 v[38:39], v[42:43], v[56:57] op_sel_hi:[1,0]
	v_add_f32_dpp v22, v15, v15 row_ror:8 row_mask:0xf bank_mask:0xf bound_ctrl:1
	v_pk_fma_f32 v[8:9], v[104:105], v[22:23], v[16:17] op_sel_hi:[1,0,1]
	v_pk_fma_f32 v[6:7], v[106:107], v[22:23], v[18:19] op_sel_hi:[1,0,1]
	v_pk_mul_f32 v[20:21], v[48:49], v[8:9]
	v_pk_fma_f32 v[20:21], v[6:7], v[50:51], v[20:21]
	ds_read_b128 v[100:103], v5 offset:28928
	ds_read_b128 v[92:95], v5 offset:12544
	ds_read_b32 v108, v14 offset:1088
	ds_read_b128 v[96:99], v5 offset:20736
	ds_read_b128 v[104:107], v5 offset:37120
	ds_read_b128 v[116:119], v5 offset:4352
	v_add_f32_e32 v15, v20, v21
	v_pk_fma_f32 v[16:17], v[8:9], v[44:45], v[36:37]
	v_pk_fma_f32 v[18:19], v[6:7], v[46:47], v[38:39]
	v_add_f32_dpp v15, v15, v15 quad_perm:[1,0,3,2] row_mask:0xf bank_mask:0xf bound_ctrl:1
	v_pk_mul_f32 v[24:25], v[120:121], v[8:9]
	v_pk_fma_f32 v[24:25], v[6:7], v[122:123], v[24:25]
	v_add_f32_dpp v15, v15, v15 quad_perm:[2,3,0,1] row_mask:0xf bank_mask:0xf bound_ctrl:1
	v_add_f32_e32 v26, v24, v25
	ds_write_b32 v0, v26 offset:3584
	v_add_f32_dpp v15, v15, v15 row_ror:4 row_mask:0xf bank_mask:0xf bound_ctrl:1
	s_waitcnt lgkmcnt(8)
	v_pk_mul_f32 v[32:33], v[60:61], v[76:77] op_sel_hi:[1,0]
	v_pk_mul_f32 v[34:35], v[62:63], v[76:77] op_sel_hi:[1,0]
	v_add_f32_dpp v22, v15, v15 row_ror:8 row_mask:0xf bank_mask:0xf bound_ctrl:1
	v_pk_fma_f32 v[8:9], v[52:53], v[22:23], v[16:17] op_sel_hi:[1,0,1]
	v_pk_fma_f32 v[6:7], v[54:55], v[22:23], v[18:19] op_sel_hi:[1,0,1]
	v_pk_mul_f32 v[20:21], v[68:69], v[8:9]
	v_pk_fma_f32 v[20:21], v[6:7], v[70:71], v[20:21]
	ds_read_b128 v[48:51], v5 offset:29184
	ds_read_b128 v[40:43], v5 offset:12800
	ds_read_b32 v56, v14 offset:1152
	ds_read_b128 v[44:47], v5 offset:20992
	ds_read_b128 v[52:55], v5 offset:37376
	ds_read_b128 v[120:123], v5 offset:4608
	v_add_f32_e32 v15, v20, v21
	v_pk_fma_f32 v[16:17], v[8:9], v[64:65], v[32:33]
	v_pk_fma_f32 v[18:19], v[6:7], v[66:67], v[34:35]
	v_add_f32_dpp v15, v15, v15 quad_perm:[1,0,3,2] row_mask:0xf bank_mask:0xf bound_ctrl:1
	v_pk_mul_f32 v[24:25], v[124:125], v[8:9]
	v_pk_fma_f32 v[24:25], v[6:7], v[126:127], v[24:25]
	v_add_f32_dpp v15, v15, v15 quad_perm:[2,3,0,1] row_mask:0xf bank_mask:0xf bound_ctrl:1
	v_add_f32_e32 v26, v24, v25
	ds_write_b32 v0, v26 offset:3840
	v_add_f32_dpp v15, v15, v15 row_ror:4 row_mask:0xf bank_mask:0xf bound_ctrl:1
	s_waitcnt lgkmcnt(8)
	v_pk_mul_f32 v[36:37], v[92:93], v[108:109] op_sel_hi:[1,0]
	v_pk_mul_f32 v[38:39], v[94:95], v[108:109] op_sel_hi:[1,0]
	v_add_f32_dpp v22, v15, v15 row_ror:8 row_mask:0xf bank_mask:0xf bound_ctrl:1
	v_pk_fma_f32 v[8:9], v[72:73], v[22:23], v[16:17] op_sel_hi:[1,0,1]
	v_pk_fma_f32 v[6:7], v[74:75], v[22:23], v[18:19] op_sel_hi:[1,0,1]
	v_pk_mul_f32 v[20:21], v[100:101], v[8:9]
	v_pk_fma_f32 v[20:21], v[6:7], v[102:103], v[20:21]
	ds_read_b128 v[68:71], v5 offset:29440
	ds_read_b128 v[60:63], v5 offset:13056
	ds_read_b32 v76, v14 offset:1216
	ds_read_b128 v[64:67], v5 offset:21248
	ds_read_b128 v[72:75], v5 offset:37632
	ds_read_b128 v[124:127], v5 offset:4864
	v_add_f32_e32 v15, v20, v21
	v_pk_fma_f32 v[16:17], v[8:9], v[96:97], v[36:37]
	v_pk_fma_f32 v[18:19], v[6:7], v[98:99], v[38:39]
	v_add_f32_dpp v15, v15, v15 quad_perm:[1,0,3,2] row_mask:0xf bank_mask:0xf bound_ctrl:1
	v_pk_mul_f32 v[24:25], v[112:113], v[8:9]
	v_pk_fma_f32 v[24:25], v[6:7], v[114:115], v[24:25]
	v_add_f32_dpp v15, v15, v15 quad_perm:[2,3,0,1] row_mask:0xf bank_mask:0xf bound_ctrl:1
	v_add_f32_e32 v26, v24, v25
	ds_write_b32 v0, v26 offset:4096
	v_add_f32_dpp v15, v15, v15 row_ror:4 row_mask:0xf bank_mask:0xf bound_ctrl:1
	s_waitcnt lgkmcnt(8)
	v_pk_mul_f32 v[32:33], v[40:41], v[56:57] op_sel_hi:[1,0]
	v_pk_mul_f32 v[34:35], v[42:43], v[56:57] op_sel_hi:[1,0]
	v_add_f32_dpp v22, v15, v15 row_ror:8 row_mask:0xf bank_mask:0xf bound_ctrl:1
	v_pk_fma_f32 v[8:9], v[104:105], v[22:23], v[16:17] op_sel_hi:[1,0,1]
	v_pk_fma_f32 v[6:7], v[106:107], v[22:23], v[18:19] op_sel_hi:[1,0,1]
	v_pk_mul_f32 v[20:21], v[48:49], v[8:9]
	v_pk_fma_f32 v[20:21], v[6:7], v[50:51], v[20:21]
	ds_read_b128 v[100:103], v5 offset:29696
	ds_read_b128 v[92:95], v5 offset:13312
	ds_read_b32 v108, v14 offset:1280
	ds_read_b128 v[96:99], v5 offset:21504
	ds_read_b128 v[104:107], v5 offset:37888
	ds_read_b128 v[112:115], v5 offset:5120
	v_add_f32_e32 v15, v20, v21
	v_pk_fma_f32 v[16:17], v[8:9], v[44:45], v[32:33]
	v_pk_fma_f32 v[18:19], v[6:7], v[46:47], v[34:35]
	v_add_f32_dpp v15, v15, v15 quad_perm:[1,0,3,2] row_mask:0xf bank_mask:0xf bound_ctrl:1
	v_pk_mul_f32 v[24:25], v[116:117], v[8:9]
	v_pk_fma_f32 v[24:25], v[6:7], v[118:119], v[24:25]
	v_add_f32_dpp v15, v15, v15 quad_perm:[2,3,0,1] row_mask:0xf bank_mask:0xf bound_ctrl:1
	v_add_f32_e32 v26, v24, v25
	ds_write_b32 v0, v26 offset:4352
	v_add_f32_dpp v15, v15, v15 row_ror:4 row_mask:0xf bank_mask:0xf bound_ctrl:1
	s_waitcnt lgkmcnt(8)
	v_pk_mul_f32 v[36:37], v[60:61], v[76:77] op_sel_hi:[1,0]
	v_pk_mul_f32 v[38:39], v[62:63], v[76:77] op_sel_hi:[1,0]
	v_add_f32_dpp v22, v15, v15 row_ror:8 row_mask:0xf bank_mask:0xf bound_ctrl:1
	v_pk_fma_f32 v[8:9], v[52:53], v[22:23], v[16:17] op_sel_hi:[1,0,1]
	v_pk_fma_f32 v[6:7], v[54:55], v[22:23], v[18:19] op_sel_hi:[1,0,1]
	v_pk_mul_f32 v[20:21], v[68:69], v[8:9]
	v_pk_fma_f32 v[20:21], v[6:7], v[70:71], v[20:21]
	ds_read_b128 v[48:51], v5 offset:29952
	ds_read_b128 v[40:43], v5 offset:13568
	ds_read_b32 v56, v14 offset:1344
	ds_read_b128 v[44:47], v5 offset:21760
	ds_read_b128 v[52:55], v5 offset:38144
	ds_read_b128 v[116:119], v5 offset:5376
	v_add_f32_e32 v15, v20, v21
	v_pk_fma_f32 v[16:17], v[8:9], v[64:65], v[36:37]
	v_pk_fma_f32 v[18:19], v[6:7], v[66:67], v[38:39]
	v_add_f32_dpp v15, v15, v15 quad_perm:[1,0,3,2] row_mask:0xf bank_mask:0xf bound_ctrl:1
	v_pk_mul_f32 v[24:25], v[120:121], v[8:9]
	v_pk_fma_f32 v[24:25], v[6:7], v[122:123], v[24:25]
	v_add_f32_dpp v15, v15, v15 quad_perm:[2,3,0,1] row_mask:0xf bank_mask:0xf bound_ctrl:1
	v_add_f32_e32 v26, v24, v25
	ds_write_b32 v0, v26 offset:4608
	v_add_f32_dpp v15, v15, v15 row_ror:4 row_mask:0xf bank_mask:0xf bound_ctrl:1
	s_waitcnt lgkmcnt(8)
	v_pk_mul_f32 v[32:33], v[92:93], v[108:109] op_sel_hi:[1,0]
	v_pk_mul_f32 v[34:35], v[94:95], v[108:109] op_sel_hi:[1,0]
	v_add_f32_dpp v22, v15, v15 row_ror:8 row_mask:0xf bank_mask:0xf bound_ctrl:1
	v_pk_fma_f32 v[8:9], v[72:73], v[22:23], v[16:17] op_sel_hi:[1,0,1]
	v_pk_fma_f32 v[6:7], v[74:75], v[22:23], v[18:19] op_sel_hi:[1,0,1]
	v_pk_mul_f32 v[20:21], v[100:101], v[8:9]
	v_pk_fma_f32 v[20:21], v[6:7], v[102:103], v[20:21]
	ds_read_b128 v[68:71], v5 offset:30208
	ds_read_b128 v[60:63], v5 offset:13824
	ds_read_b32 v76, v14 offset:1408
	ds_read_b128 v[64:67], v5 offset:22016
	ds_read_b128 v[72:75], v5 offset:38400
	ds_read_b128 v[120:123], v5 offset:5632
	v_add_f32_e32 v15, v20, v21
	v_pk_fma_f32 v[16:17], v[8:9], v[96:97], v[32:33]
	v_pk_fma_f32 v[18:19], v[6:7], v[98:99], v[34:35]
	v_add_f32_dpp v15, v15, v15 quad_perm:[1,0,3,2] row_mask:0xf bank_mask:0xf bound_ctrl:1
	v_pk_mul_f32 v[24:25], v[124:125], v[8:9]
	v_pk_fma_f32 v[24:25], v[6:7], v[126:127], v[24:25]
	v_add_f32_dpp v15, v15, v15 quad_perm:[2,3,0,1] row_mask:0xf bank_mask:0xf bound_ctrl:1
	v_add_f32_e32 v26, v24, v25
	ds_write_b32 v0, v26 offset:4864
	v_add_f32_dpp v15, v15, v15 row_ror:4 row_mask:0xf bank_mask:0xf bound_ctrl:1
	s_waitcnt lgkmcnt(8)
	v_pk_mul_f32 v[36:37], v[40:41], v[56:57] op_sel_hi:[1,0]
	v_pk_mul_f32 v[38:39], v[42:43], v[56:57] op_sel_hi:[1,0]
	v_add_f32_dpp v22, v15, v15 row_ror:8 row_mask:0xf bank_mask:0xf bound_ctrl:1
	v_pk_fma_f32 v[8:9], v[104:105], v[22:23], v[16:17] op_sel_hi:[1,0,1]
	v_pk_fma_f32 v[6:7], v[106:107], v[22:23], v[18:19] op_sel_hi:[1,0,1]
	v_pk_mul_f32 v[20:21], v[48:49], v[8:9]
	v_pk_fma_f32 v[20:21], v[6:7], v[50:51], v[20:21]
	ds_read_b128 v[100:103], v5 offset:30464
	ds_read_b128 v[92:95], v5 offset:14080
	ds_read_b32 v108, v14 offset:1472
	ds_read_b128 v[96:99], v5 offset:22272
	ds_read_b128 v[104:107], v5 offset:38656
	ds_read_b128 v[124:127], v5 offset:5888
	v_add_f32_e32 v15, v20, v21
	v_pk_fma_f32 v[16:17], v[8:9], v[44:45], v[36:37]
	v_pk_fma_f32 v[18:19], v[6:7], v[46:47], v[38:39]
	v_add_f32_dpp v15, v15, v15 quad_perm:[1,0,3,2] row_mask:0xf bank_mask:0xf bound_ctrl:1
	v_pk_mul_f32 v[24:25], v[112:113], v[8:9]
	v_pk_fma_f32 v[24:25], v[6:7], v[114:115], v[24:25]
	v_add_f32_dpp v15, v15, v15 quad_perm:[2,3,0,1] row_mask:0xf bank_mask:0xf bound_ctrl:1
	v_add_f32_e32 v26, v24, v25
	ds_write_b32 v0, v26 offset:5120
	v_add_f32_dpp v15, v15, v15 row_ror:4 row_mask:0xf bank_mask:0xf bound_ctrl:1
	s_waitcnt lgkmcnt(8)
	v_pk_mul_f32 v[32:33], v[60:61], v[76:77] op_sel_hi:[1,0]
	v_pk_mul_f32 v[34:35], v[62:63], v[76:77] op_sel_hi:[1,0]
	v_add_f32_dpp v22, v15, v15 row_ror:8 row_mask:0xf bank_mask:0xf bound_ctrl:1
	v_pk_fma_f32 v[8:9], v[52:53], v[22:23], v[16:17] op_sel_hi:[1,0,1]
	v_pk_fma_f32 v[6:7], v[54:55], v[22:23], v[18:19] op_sel_hi:[1,0,1]
	v_pk_mul_f32 v[20:21], v[68:69], v[8:9]
	v_pk_fma_f32 v[20:21], v[6:7], v[70:71], v[20:21]
	ds_read_b128 v[48:51], v5 offset:30720
	ds_read_b128 v[40:43], v5 offset:14336
	ds_read_b32 v56, v14 offset:1536
	ds_read_b128 v[44:47], v5 offset:22528
	ds_read_b128 v[52:55], v5 offset:38912
	ds_read_b128 v[112:115], v5 offset:6144
	v_add_f32_e32 v15, v20, v21
	v_pk_fma_f32 v[16:17], v[8:9], v[64:65], v[32:33]
	v_pk_fma_f32 v[18:19], v[6:7], v[66:67], v[34:35]
	v_add_f32_dpp v15, v15, v15 quad_perm:[1,0,3,2] row_mask:0xf bank_mask:0xf bound_ctrl:1
	v_pk_mul_f32 v[24:25], v[116:117], v[8:9]
	v_pk_fma_f32 v[24:25], v[6:7], v[118:119], v[24:25]
	v_add_f32_dpp v15, v15, v15 quad_perm:[2,3,0,1] row_mask:0xf bank_mask:0xf bound_ctrl:1
	v_add_f32_e32 v26, v24, v25
	ds_write_b32 v0, v26 offset:5376
	v_add_f32_dpp v15, v15, v15 row_ror:4 row_mask:0xf bank_mask:0xf bound_ctrl:1
	s_waitcnt lgkmcnt(8)
	v_pk_mul_f32 v[36:37], v[92:93], v[108:109] op_sel_hi:[1,0]
	v_pk_mul_f32 v[38:39], v[94:95], v[108:109] op_sel_hi:[1,0]
	v_add_f32_dpp v22, v15, v15 row_ror:8 row_mask:0xf bank_mask:0xf bound_ctrl:1
	v_pk_fma_f32 v[8:9], v[72:73], v[22:23], v[16:17] op_sel_hi:[1,0,1]
	v_pk_fma_f32 v[6:7], v[74:75], v[22:23], v[18:19] op_sel_hi:[1,0,1]
	v_pk_mul_f32 v[20:21], v[100:101], v[8:9]
	v_pk_fma_f32 v[20:21], v[6:7], v[102:103], v[20:21]
	ds_read_b128 v[68:71], v5 offset:30976
	ds_read_b128 v[60:63], v5 offset:14592
	ds_read_b32 v76, v14 offset:1600
	ds_read_b128 v[64:67], v5 offset:22784
	ds_read_b128 v[72:75], v5 offset:39168
	ds_read_b128 v[116:119], v5 offset:6400
	v_add_f32_e32 v15, v20, v21
	v_pk_fma_f32 v[16:17], v[8:9], v[96:97], v[36:37]
	v_pk_fma_f32 v[18:19], v[6:7], v[98:99], v[38:39]
	v_add_f32_dpp v15, v15, v15 quad_perm:[1,0,3,2] row_mask:0xf bank_mask:0xf bound_ctrl:1
	v_pk_mul_f32 v[24:25], v[120:121], v[8:9]
	v_pk_fma_f32 v[24:25], v[6:7], v[122:123], v[24:25]
	v_add_f32_dpp v15, v15, v15 quad_perm:[2,3,0,1] row_mask:0xf bank_mask:0xf bound_ctrl:1
	v_add_f32_e32 v26, v24, v25
	ds_write_b32 v0, v26 offset:5632
	v_add_f32_dpp v15, v15, v15 row_ror:4 row_mask:0xf bank_mask:0xf bound_ctrl:1
	s_waitcnt lgkmcnt(8)
	v_pk_mul_f32 v[32:33], v[40:41], v[56:57] op_sel_hi:[1,0]
	v_pk_mul_f32 v[34:35], v[42:43], v[56:57] op_sel_hi:[1,0]
	v_add_f32_dpp v22, v15, v15 row_ror:8 row_mask:0xf bank_mask:0xf bound_ctrl:1
	v_pk_fma_f32 v[8:9], v[104:105], v[22:23], v[16:17] op_sel_hi:[1,0,1]
	v_pk_fma_f32 v[6:7], v[106:107], v[22:23], v[18:19] op_sel_hi:[1,0,1]
	v_pk_mul_f32 v[20:21], v[48:49], v[8:9]
	v_pk_fma_f32 v[20:21], v[6:7], v[50:51], v[20:21]
	ds_read_b128 v[100:103], v5 offset:31232
	ds_read_b128 v[92:95], v5 offset:14848
	ds_read_b32 v108, v14 offset:1664
	ds_read_b128 v[96:99], v5 offset:23040
	ds_read_b128 v[104:107], v5 offset:39424
	ds_read_b128 v[120:123], v5 offset:6656
	v_add_f32_e32 v15, v20, v21
	v_pk_fma_f32 v[16:17], v[8:9], v[44:45], v[32:33]
	v_pk_fma_f32 v[18:19], v[6:7], v[46:47], v[34:35]
	v_add_f32_dpp v15, v15, v15 quad_perm:[1,0,3,2] row_mask:0xf bank_mask:0xf bound_ctrl:1
	v_pk_mul_f32 v[24:25], v[124:125], v[8:9]
	v_pk_fma_f32 v[24:25], v[6:7], v[126:127], v[24:25]
	v_add_f32_dpp v15, v15, v15 quad_perm:[2,3,0,1] row_mask:0xf bank_mask:0xf bound_ctrl:1
	v_add_f32_e32 v26, v24, v25
	ds_write_b32 v0, v26 offset:5888
	v_add_f32_dpp v15, v15, v15 row_ror:4 row_mask:0xf bank_mask:0xf bound_ctrl:1
	s_waitcnt lgkmcnt(8)
	v_pk_mul_f32 v[36:37], v[60:61], v[76:77] op_sel_hi:[1,0]
	v_pk_mul_f32 v[38:39], v[62:63], v[76:77] op_sel_hi:[1,0]
	v_add_f32_dpp v22, v15, v15 row_ror:8 row_mask:0xf bank_mask:0xf bound_ctrl:1
	v_pk_fma_f32 v[8:9], v[52:53], v[22:23], v[16:17] op_sel_hi:[1,0,1]
	v_pk_fma_f32 v[6:7], v[54:55], v[22:23], v[18:19] op_sel_hi:[1,0,1]
	v_pk_mul_f32 v[20:21], v[68:69], v[8:9]
	v_pk_fma_f32 v[20:21], v[6:7], v[70:71], v[20:21]
	ds_read_b128 v[48:51], v5 offset:31488
	ds_read_b128 v[40:43], v5 offset:15104
	ds_read_b32 v56, v14 offset:1728
	ds_read_b128 v[44:47], v5 offset:23296
	ds_read_b128 v[52:55], v5 offset:39680
	ds_read_b128 v[124:127], v5 offset:6912
	v_add_f32_e32 v15, v20, v21
	v_pk_fma_f32 v[16:17], v[8:9], v[64:65], v[36:37]
	v_pk_fma_f32 v[18:19], v[6:7], v[66:67], v[38:39]
	v_add_f32_dpp v15, v15, v15 quad_perm:[1,0,3,2] row_mask:0xf bank_mask:0xf bound_ctrl:1
	v_pk_mul_f32 v[24:25], v[112:113], v[8:9]
	v_pk_fma_f32 v[24:25], v[6:7], v[114:115], v[24:25]
	v_add_f32_dpp v15, v15, v15 quad_perm:[2,3,0,1] row_mask:0xf bank_mask:0xf bound_ctrl:1
	v_add_f32_e32 v26, v24, v25
	ds_write_b32 v0, v26 offset:6144
	v_add_f32_dpp v15, v15, v15 row_ror:4 row_mask:0xf bank_mask:0xf bound_ctrl:1
	s_waitcnt lgkmcnt(8)
	v_pk_mul_f32 v[32:33], v[92:93], v[108:109] op_sel_hi:[1,0]
	v_pk_mul_f32 v[34:35], v[94:95], v[108:109] op_sel_hi:[1,0]
	v_add_f32_dpp v22, v15, v15 row_ror:8 row_mask:0xf bank_mask:0xf bound_ctrl:1
	v_pk_fma_f32 v[8:9], v[72:73], v[22:23], v[16:17] op_sel_hi:[1,0,1]
	v_pk_fma_f32 v[6:7], v[74:75], v[22:23], v[18:19] op_sel_hi:[1,0,1]
	v_pk_mul_f32 v[20:21], v[100:101], v[8:9]
	v_pk_fma_f32 v[20:21], v[6:7], v[102:103], v[20:21]
	ds_read_b128 v[68:71], v5 offset:31744
	ds_read_b128 v[60:63], v5 offset:15360
	ds_read_b32 v76, v14 offset:1792
	ds_read_b128 v[64:67], v5 offset:23552
	ds_read_b128 v[72:75], v5 offset:39936
	ds_read_b128 v[112:115], v5 offset:7168
	v_add_f32_e32 v15, v20, v21
	v_pk_fma_f32 v[16:17], v[8:9], v[96:97], v[32:33]
	v_pk_fma_f32 v[18:19], v[6:7], v[98:99], v[34:35]
	v_add_f32_dpp v15, v15, v15 quad_perm:[1,0,3,2] row_mask:0xf bank_mask:0xf bound_ctrl:1
	v_pk_mul_f32 v[24:25], v[116:117], v[8:9]
	v_pk_fma_f32 v[24:25], v[6:7], v[118:119], v[24:25]
	v_add_f32_dpp v15, v15, v15 quad_perm:[2,3,0,1] row_mask:0xf bank_mask:0xf bound_ctrl:1
	v_add_f32_e32 v26, v24, v25
	ds_write_b32 v0, v26 offset:6400
	v_add_f32_dpp v15, v15, v15 row_ror:4 row_mask:0xf bank_mask:0xf bound_ctrl:1
	s_waitcnt lgkmcnt(8)
	v_pk_mul_f32 v[36:37], v[40:41], v[56:57] op_sel_hi:[1,0]
	v_pk_mul_f32 v[38:39], v[42:43], v[56:57] op_sel_hi:[1,0]
	v_add_f32_dpp v22, v15, v15 row_ror:8 row_mask:0xf bank_mask:0xf bound_ctrl:1
	v_pk_fma_f32 v[8:9], v[104:105], v[22:23], v[16:17] op_sel_hi:[1,0,1]
	v_pk_fma_f32 v[6:7], v[106:107], v[22:23], v[18:19] op_sel_hi:[1,0,1]
	v_pk_mul_f32 v[20:21], v[48:49], v[8:9]
	v_pk_fma_f32 v[20:21], v[6:7], v[50:51], v[20:21]
	ds_read_b128 v[100:103], v5 offset:32000
	ds_read_b128 v[92:95], v5 offset:15616
	ds_read_b32 v108, v14 offset:1856
	ds_read_b128 v[96:99], v5 offset:23808
	ds_read_b128 v[104:107], v5 offset:40192
	ds_read_b128 v[116:119], v5 offset:7424
	v_add_f32_e32 v15, v20, v21
	v_pk_fma_f32 v[16:17], v[8:9], v[44:45], v[36:37]
	v_pk_fma_f32 v[18:19], v[6:7], v[46:47], v[38:39]
	v_add_f32_dpp v15, v15, v15 quad_perm:[1,0,3,2] row_mask:0xf bank_mask:0xf bound_ctrl:1
	v_pk_mul_f32 v[24:25], v[120:121], v[8:9]
	v_pk_fma_f32 v[24:25], v[6:7], v[122:123], v[24:25]
	v_add_f32_dpp v15, v15, v15 quad_perm:[2,3,0,1] row_mask:0xf bank_mask:0xf bound_ctrl:1
	v_add_f32_e32 v26, v24, v25
	ds_write_b32 v0, v26 offset:6656
	v_add_f32_dpp v15, v15, v15 row_ror:4 row_mask:0xf bank_mask:0xf bound_ctrl:1
	s_waitcnt lgkmcnt(8)
	v_pk_mul_f32 v[32:33], v[60:61], v[76:77] op_sel_hi:[1,0]
	v_pk_mul_f32 v[34:35], v[62:63], v[76:77] op_sel_hi:[1,0]
	v_add_f32_dpp v22, v15, v15 row_ror:8 row_mask:0xf bank_mask:0xf bound_ctrl:1
	v_pk_fma_f32 v[8:9], v[52:53], v[22:23], v[16:17] op_sel_hi:[1,0,1]
	v_pk_fma_f32 v[6:7], v[54:55], v[22:23], v[18:19] op_sel_hi:[1,0,1]
	v_pk_mul_f32 v[20:21], v[68:69], v[8:9]
	v_pk_fma_f32 v[20:21], v[6:7], v[70:71], v[20:21]
	ds_read_b128 v[48:51], v5 offset:32256
	ds_read_b128 v[40:43], v5 offset:15872
	ds_read_b32 v56, v14 offset:1920
	ds_read_b128 v[44:47], v5 offset:24064
	ds_read_b128 v[52:55], v5 offset:40448
	ds_read_b128 v[120:123], v5 offset:7680
	v_add_f32_e32 v15, v20, v21
	v_pk_fma_f32 v[16:17], v[8:9], v[64:65], v[32:33]
	v_pk_fma_f32 v[18:19], v[6:7], v[66:67], v[34:35]
	v_add_f32_dpp v15, v15, v15 quad_perm:[1,0,3,2] row_mask:0xf bank_mask:0xf bound_ctrl:1
	v_pk_mul_f32 v[24:25], v[124:125], v[8:9]
	v_pk_fma_f32 v[24:25], v[6:7], v[126:127], v[24:25]
	v_add_f32_dpp v15, v15, v15 quad_perm:[2,3,0,1] row_mask:0xf bank_mask:0xf bound_ctrl:1
	v_add_f32_e32 v26, v24, v25
	ds_write_b32 v0, v26 offset:6912
	v_add_f32_dpp v15, v15, v15 row_ror:4 row_mask:0xf bank_mask:0xf bound_ctrl:1
	s_waitcnt lgkmcnt(8)
	v_pk_mul_f32 v[36:37], v[92:93], v[108:109] op_sel_hi:[1,0]
	v_pk_mul_f32 v[38:39], v[94:95], v[108:109] op_sel_hi:[1,0]
	v_add_f32_dpp v22, v15, v15 row_ror:8 row_mask:0xf bank_mask:0xf bound_ctrl:1
	v_pk_fma_f32 v[8:9], v[72:73], v[22:23], v[16:17] op_sel_hi:[1,0,1]
	v_pk_fma_f32 v[6:7], v[74:75], v[22:23], v[18:19] op_sel_hi:[1,0,1]
	v_pk_mul_f32 v[20:21], v[100:101], v[8:9]
	v_pk_fma_f32 v[20:21], v[6:7], v[102:103], v[20:21]
	ds_read_b128 v[68:71], v5 offset:32512
	ds_read_b128 v[60:63], v5 offset:16128
	ds_read_b32 v76, v14 offset:1984
	ds_read_b128 v[64:67], v5 offset:24320
	ds_read_b128 v[72:75], v5 offset:40704
	ds_read_b128 v[124:127], v5 offset:7936
	v_add_f32_e32 v15, v20, v21
	v_pk_fma_f32 v[16:17], v[8:9], v[96:97], v[36:37]
	v_pk_fma_f32 v[18:19], v[6:7], v[98:99], v[38:39]
	v_add_f32_dpp v15, v15, v15 quad_perm:[1,0,3,2] row_mask:0xf bank_mask:0xf bound_ctrl:1
	v_pk_mul_f32 v[24:25], v[112:113], v[8:9]
	v_pk_fma_f32 v[24:25], v[6:7], v[114:115], v[24:25]
	v_add_f32_dpp v15, v15, v15 quad_perm:[2,3,0,1] row_mask:0xf bank_mask:0xf bound_ctrl:1
	v_add_f32_e32 v26, v24, v25
	ds_write_b32 v0, v26 offset:7168
	v_add_f32_dpp v15, v15, v15 row_ror:4 row_mask:0xf bank_mask:0xf bound_ctrl:1
	s_waitcnt lgkmcnt(8)
	v_pk_mul_f32 v[32:33], v[40:41], v[56:57] op_sel_hi:[1,0]
	v_pk_mul_f32 v[34:35], v[42:43], v[56:57] op_sel_hi:[1,0]
	v_add_f32_dpp v22, v15, v15 row_ror:8 row_mask:0xf bank_mask:0xf bound_ctrl:1
	v_pk_fma_f32 v[8:9], v[104:105], v[22:23], v[16:17] op_sel_hi:[1,0,1]
	v_pk_fma_f32 v[6:7], v[106:107], v[22:23], v[18:19] op_sel_hi:[1,0,1]
	v_pk_mul_f32 v[20:21], v[48:49], v[8:9]
	v_pk_fma_f32 v[20:21], v[6:7], v[50:51], v[20:21]
	v_add_f32_e32 v15, v20, v21
	v_pk_fma_f32 v[16:17], v[8:9], v[44:45], v[32:33]
	v_pk_fma_f32 v[18:19], v[6:7], v[46:47], v[34:35]
	v_add_f32_dpp v15, v15, v15 quad_perm:[1,0,3,2] row_mask:0xf bank_mask:0xf bound_ctrl:1
	v_pk_mul_f32 v[24:25], v[116:117], v[8:9]
	v_pk_fma_f32 v[24:25], v[6:7], v[118:119], v[24:25]
	v_add_f32_dpp v15, v15, v15 quad_perm:[2,3,0,1] row_mask:0xf bank_mask:0xf bound_ctrl:1
	v_add_f32_e32 v26, v24, v25
	ds_write_b32 v0, v26 offset:7424
	v_add_f32_dpp v15, v15, v15 row_ror:4 row_mask:0xf bank_mask:0xf bound_ctrl:1
	s_waitcnt lgkmcnt(2)
	v_pk_mul_f32 v[36:37], v[60:61], v[76:77] op_sel_hi:[1,0]
	v_pk_mul_f32 v[38:39], v[62:63], v[76:77] op_sel_hi:[1,0]
	v_add_f32_dpp v22, v15, v15 row_ror:8 row_mask:0xf bank_mask:0xf bound_ctrl:1
	v_pk_fma_f32 v[8:9], v[52:53], v[22:23], v[16:17] op_sel_hi:[1,0,1]
	v_pk_fma_f32 v[6:7], v[54:55], v[22:23], v[18:19] op_sel_hi:[1,0,1]
	v_pk_mul_f32 v[20:21], v[68:69], v[8:9]
	v_pk_fma_f32 v[20:21], v[6:7], v[70:71], v[20:21]
	v_add_f32_e32 v15, v20, v21
	v_pk_fma_f32 v[16:17], v[8:9], v[64:65], v[36:37]
	v_pk_fma_f32 v[18:19], v[6:7], v[66:67], v[38:39]
	v_add_f32_dpp v15, v15, v15 quad_perm:[1,0,3,2] row_mask:0xf bank_mask:0xf bound_ctrl:1
	v_pk_mul_f32 v[24:25], v[120:121], v[8:9]
	v_pk_fma_f32 v[24:25], v[6:7], v[122:123], v[24:25]
	v_add_f32_dpp v15, v15, v15 quad_perm:[2,3,0,1] row_mask:0xf bank_mask:0xf bound_ctrl:1
	v_add_f32_e32 v26, v24, v25
	ds_write_b32 v0, v26 offset:7680
	v_add_f32_dpp v15, v15, v15 row_ror:4 row_mask:0xf bank_mask:0xf bound_ctrl:1
	s_nop 1
	v_add_f32_dpp v22, v15, v15 row_ror:8 row_mask:0xf bank_mask:0xf bound_ctrl:1
	v_pk_fma_f32 v[8:9], v[72:73], v[22:23], v[16:17] op_sel_hi:[1,0,1]
	v_pk_fma_f32 v[6:7], v[74:75], v[22:23], v[18:19] op_sel_hi:[1,0,1]
	v_pk_mul_f32 v[24:25], v[124:125], v[8:9]
	v_pk_fma_f32 v[24:25], v[6:7], v[126:127], v[24:25]
	v_add_u32_e32 v30, -16, v4
	v_ashrrev_i32_e32 v31, 31, v30
	v_add_f32_e32 v26, v24, v25
	ds_write_b32 v0, v26 offset:7936
	v_lshlrev_b64 v[30:31], 11, v[30:31]
	s_nop 0
	v_lshl_add_u64 v[30:31], v[2:3], 0, v[30:31]
	v_mov_b32_e32 v0, v12
	s_waitcnt lgkmcnt(0)
	s_nop 0
	v_add_u32_e32 v0, 0, v0
	ds_read_b128 v[14:17], v0
	ds_read_b128 v[18:21], v0 offset:16
	ds_read_b128 v[22:25], v0 offset:32
	ds_read_b128 v[26:29], v0 offset:48
	s_waitcnt lgkmcnt(2)
	v_pk_add_f32 v[16:17], v[16:17], v[20:21]
	v_pk_add_f32 v[14:15], v[14:15], v[18:19]
	s_waitcnt lgkmcnt(0)
	v_pk_add_f32 v[18:19], v[24:25], v[28:29]
	v_pk_add_f32 v[20:21], v[22:23], v[26:27]
	v_pk_add_f32 v[16:17], v[16:17], v[18:19]
	v_pk_add_f32 v[14:15], v[14:15], v[20:21]
	s_nop 0
	v_add_f32_e32 v5, v14, v15
	v_add_f32_e32 v14, v16, v17
	v_add_f32_e32 v5, v5, v14
	ds_read_b128 v[14:17], v0 offset:4096
	ds_read_b128 v[18:21], v0 offset:4112
	ds_read_b128 v[22:25], v0 offset:4128
	ds_read_b128 v[26:29], v0 offset:4144
	v_cvt_pk_bf16_f32 v5, v5, s0
	global_store_short v[30:31], v5, off
	s_waitcnt lgkmcnt(2)
	v_pk_add_f32 v[16:17], v[16:17], v[20:21]
	v_pk_add_f32 v[14:15], v[14:15], v[18:19]
	s_waitcnt lgkmcnt(0)
	v_pk_add_f32 v[18:19], v[24:25], v[28:29]
	v_pk_add_f32 v[20:21], v[22:23], v[26:27]
	v_pk_add_f32 v[16:17], v[16:17], v[18:19]
	v_pk_add_f32 v[14:15], v[14:15], v[20:21]
	v_add_f32_e32 v5, v16, v17
	v_add_f32_e32 v0, v14, v15
	v_add_f32_e32 v0, v0, v5
	v_ashrrev_i32_e32 v5, 31, v4
	v_lshlrev_b64 v[14:15], 11, v[4:5]
	v_cvt_pk_bf16_f32 v0, v0, s0
	v_lshl_add_u64 v[14:15], v[2:3], 0, v[14:15]
	global_store_short v[14:15], v0, off
	s_waitcnt lgkmcnt(0)
	s_branch .LBB0_905
